# first-iteration peel (zero SrcC, no accumulator zeroing) extended to the down, w_o, dq and uq GEMM loops
# baseline (speedup 1.0000x reference)
.LBB0_1622:
	s_add_u32 s33, s22, 0x100
	s_addc_u32 s44, s23, 0
	s_mov_b32 s45, -2
	s_waitcnt vmcnt(0)
	v_add_u32_e32 v216, 0x10000, v196
	v_add_u32_e32 v217, 0x14000, v196
	v_add_u32_e32 v218, 0x18000, v196
	v_add_u32_e32 v219, 0x1c000, v196
	s_add_u32 s22, s20, 0x100
	s_addc_u32 s23, s21, 0
	s_add_i32 s46, 0, 0x10000
	ds_read_b128 v[128:131], v216
	ds_read_b128 v[132:135], v216 offset:1024
	ds_read_b128 v[136:139], v216 offset:2048
	ds_read_b128 v[140:143], v216 offset:3072
	s_cmp_eq_u32 s45, 40
	s_cselect_b32 s27, s7, s23
	s_cselect_b32 s26, s6, s22
	s_cselect_b32 s25, s9, s44
	s_cselect_b32 s24, s8, s33
	s_add_i32 m0, s34, 0xc000
	ds_read_b128 v[144:147], v198
	ds_read_b128 v[148:151], v198 offset:1024
	ds_read_b128 v[152:155], v198 offset:2048
	ds_read_b128 v[156:159], v198 offset:3072
	ds_read_b128 v[160:163], v198 offset:4096
	ds_read_b128 v[164:167], v198 offset:5120
	ds_read_b128 v[168:171], v198 offset:6144
	ds_read_b128 v[172:175], v198 offset:7168
	global_load_lds_dwordx4 v214, s[20:21]
	s_add_i32 m0, s34, 0xe000
	s_nop 0
	global_load_lds_dwordx4 v212, s[20:21]
	s_waitcnt lgkmcnt(8)
	s_barrier
	s_waitcnt lgkmcnt(0)
	v_mfma_f32_16x16x32_bf16 v[124:127], v[128:131], v[144:147], 0
	v_mfma_f32_16x16x32_bf16 v[120:123], v[136:139], v[144:147], 0
	v_mfma_f32_16x16x32_bf16 v[108:111], v[128:131], v[152:155], 0
	v_mfma_f32_16x16x32_bf16 v[104:107], v[136:139], v[152:155], 0
	v_mfma_f32_16x16x32_bf16 v[92:95], v[128:131], v[160:163], 0
	v_mfma_f32_16x16x32_bf16 v[88:91], v[136:139], v[160:163], 0
	v_mfma_f32_16x16x32_bf16 v[76:79], v[128:131], v[168:171], 0
	v_mfma_f32_16x16x32_bf16 v[72:75], v[136:139], v[168:171], 0
	v_mfma_f32_16x16x32_bf16 v[124:127], v[132:135], v[148:151], v[124:127]
	v_mfma_f32_16x16x32_bf16 v[120:123], v[140:143], v[148:151], v[120:123]
	v_mfma_f32_16x16x32_bf16 v[108:111], v[132:135], v[156:159], v[108:111]
	v_mfma_f32_16x16x32_bf16 v[104:107], v[140:143], v[156:159], v[104:107]
	v_mfma_f32_16x16x32_bf16 v[92:95], v[132:135], v[164:167], v[92:95]
	v_mfma_f32_16x16x32_bf16 v[88:91], v[140:143], v[164:167], v[88:91]
	v_mfma_f32_16x16x32_bf16 v[76:79], v[132:135], v[172:175], v[76:79]
	v_mfma_f32_16x16x32_bf16 v[72:75], v[140:143], v[172:175], v[72:75]
	s_barrier
	s_add_i32 s47, 0, 0x14000
	s_add_i32 s20, s46, s31
	s_mov_b32 m0, s20
	ds_read_b128 v[176:179], v217
	ds_read_b128 v[180:183], v217 offset:1024
	ds_read_b128 v[184:187], v217 offset:2048
	ds_read_b128 v[188:191], v217 offset:3072
	global_load_lds_dwordx4 v192, s[24:25]
	s_add_i32 m0, s20, 0x2000
	s_nop 0
	global_load_lds_dwordx4 v210, s[24:25]
	s_barrier
	s_waitcnt lgkmcnt(0)
	v_mfma_f32_16x16x32_bf16 v[116:119], v[176:179], v[144:147], 0
	v_mfma_f32_16x16x32_bf16 v[112:115], v[184:187], v[144:147], 0
	v_mfma_f32_16x16x32_bf16 v[100:103], v[176:179], v[152:155], 0
	v_mfma_f32_16x16x32_bf16 v[96:99], v[184:187], v[152:155], 0
	v_mfma_f32_16x16x32_bf16 v[84:87], v[176:179], v[160:163], 0
	v_mfma_f32_16x16x32_bf16 v[80:83], v[184:187], v[160:163], 0
	v_mfma_f32_16x16x32_bf16 v[68:71], v[176:179], v[168:171], 0
	v_mfma_f32_16x16x32_bf16 v[64:67], v[184:187], v[168:171], 0
	v_mfma_f32_16x16x32_bf16 v[116:119], v[180:183], v[148:151], v[116:119]
	v_mfma_f32_16x16x32_bf16 v[112:115], v[188:191], v[148:151], v[112:115]
	v_mfma_f32_16x16x32_bf16 v[100:103], v[180:183], v[156:159], v[100:103]
	v_mfma_f32_16x16x32_bf16 v[96:99], v[188:191], v[156:159], v[96:99]
	v_mfma_f32_16x16x32_bf16 v[84:87], v[180:183], v[164:167], v[84:87]
	v_mfma_f32_16x16x32_bf16 v[80:83], v[188:191], v[164:167], v[80:83]
	v_mfma_f32_16x16x32_bf16 v[68:71], v[180:183], v[172:175], v[68:71]
	v_mfma_f32_16x16x32_bf16 v[64:67], v[188:191], v[172:175], v[64:67]
	s_mov_b32 m0, s34
	s_add_u32 vcc_lo, s26, 0x80
	s_addc_u32 vcc_hi, s27, 0
	s_barrier
	ds_read_b128 v[144:147], v198 offset:16384
	ds_read_b128 v[148:151], v198 offset:17408
	ds_read_b128 v[152:155], v198 offset:18432
	ds_read_b128 v[156:159], v198 offset:19456
	ds_read_b128 v[160:163], v198 offset:20480
	ds_read_b128 v[164:167], v198 offset:21504
	ds_read_b128 v[168:171], v198 offset:22528
	ds_read_b128 v[172:175], v198 offset:23552
	global_load_lds_dwordx4 v206, s[26:27]
	s_mov_b32 m0, s35
	s_nop 0
	global_load_lds_dwordx4 v208, s[26:27]
	s_barrier
	s_waitcnt lgkmcnt(0)
	v_mfma_f32_16x16x32_bf16 v[60:63], v[128:131], v[144:147], 0
	v_mfma_f32_16x16x32_bf16 v[56:59], v[136:139], v[144:147], 0
	v_mfma_f32_16x16x32_bf16 v[44:47], v[128:131], v[152:155], 0
	v_mfma_f32_16x16x32_bf16 v[40:43], v[136:139], v[152:155], 0
	v_mfma_f32_16x16x32_bf16 v[28:31], v[128:131], v[160:163], 0
	v_mfma_f32_16x16x32_bf16 v[24:27], v[136:139], v[160:163], 0
	v_mfma_f32_16x16x32_bf16 v[12:15], v[128:131], v[168:171], 0
	v_mfma_f32_16x16x32_bf16 v[8:11], v[136:139], v[168:171], 0
	v_mfma_f32_16x16x32_bf16 v[60:63], v[132:135], v[148:151], v[60:63]
	v_mfma_f32_16x16x32_bf16 v[56:59], v[140:143], v[148:151], v[56:59]
	v_mfma_f32_16x16x32_bf16 v[44:47], v[132:135], v[156:159], v[44:47]
	v_mfma_f32_16x16x32_bf16 v[40:43], v[140:143], v[156:159], v[40:43]
	v_mfma_f32_16x16x32_bf16 v[28:31], v[132:135], v[164:167], v[28:31]
	v_mfma_f32_16x16x32_bf16 v[24:27], v[140:143], v[164:167], v[24:27]
	v_mfma_f32_16x16x32_bf16 v[12:15], v[132:135], v[172:175], v[12:15]
	v_mfma_f32_16x16x32_bf16 v[8:11], v[140:143], v[172:175], v[8:11]
	s_barrier
	s_add_u32 s20, s24, 0xb0000
	s_addc_u32 s21, s25, 0
	s_add_i32 s46, s47, s31
	s_mov_b32 m0, s46
	s_nop 0
	global_load_lds_dwordx4 v192, s[20:21]
	s_add_i32 m0, s46, 0x2000
	s_nop 0
	global_load_lds_dwordx4 v210, s[20:21]
	s_waitcnt vmcnt(6)
	s_barrier
	v_mfma_f32_16x16x32_bf16 v[52:55], v[176:179], v[144:147], 0
	v_mfma_f32_16x16x32_bf16 v[48:51], v[184:187], v[144:147], 0
	v_mfma_f32_16x16x32_bf16 v[36:39], v[176:179], v[152:155], 0
	v_mfma_f32_16x16x32_bf16 v[32:35], v[184:187], v[152:155], 0
	v_mfma_f32_16x16x32_bf16 v[20:23], v[176:179], v[160:163], 0
	v_mfma_f32_16x16x32_bf16 v[16:19], v[184:187], v[160:163], 0
	v_mfma_f32_16x16x32_bf16 v[4:7], v[176:179], v[168:171], 0
	v_mfma_f32_16x16x32_bf16 v[0:3], v[184:187], v[168:171], 0
	v_mfma_f32_16x16x32_bf16 v[52:55], v[180:183], v[148:151], v[52:55]
	v_mfma_f32_16x16x32_bf16 v[48:51], v[188:191], v[148:151], v[48:51]
	v_mfma_f32_16x16x32_bf16 v[36:39], v[180:183], v[156:159], v[36:39]
	v_mfma_f32_16x16x32_bf16 v[32:35], v[188:191], v[156:159], v[32:35]
	v_mfma_f32_16x16x32_bf16 v[20:23], v[180:183], v[164:167], v[20:23]
	v_mfma_f32_16x16x32_bf16 v[16:19], v[188:191], v[164:167], v[16:19]
	v_mfma_f32_16x16x32_bf16 v[4:7], v[180:183], v[172:175], v[4:7]
	v_mfma_f32_16x16x32_bf16 v[0:3], v[188:191], v[172:175], v[0:3]
	s_add_i32 s46, 0, 0x18000
	s_barrier
	ds_read_b128 v[128:131], v218
	ds_read_b128 v[132:135], v218 offset:1024
	ds_read_b128 v[136:139], v218 offset:2048
	ds_read_b128 v[140:143], v218 offset:3072
	s_add_u32 s20, s26, 0xb0000
	s_addc_u32 s21, s27, 0
	s_mov_b32 m0, s36
	ds_read_b128 v[144:147], v198 offset:32768
	ds_read_b128 v[148:151], v198 offset:33792
	ds_read_b128 v[152:155], v198 offset:34816
	ds_read_b128 v[156:159], v198 offset:35840
	ds_read_b128 v[160:163], v198 offset:36864
	ds_read_b128 v[164:167], v198 offset:37888
	ds_read_b128 v[168:171], v198 offset:38912
	ds_read_b128 v[172:175], v198 offset:39936
	global_load_lds_dwordx4 v206, s[20:21]
	s_mov_b32 m0, s37
	s_nop 0
	global_load_lds_dwordx4 v208, s[20:21]
	s_waitcnt lgkmcnt(8)
	s_barrier
	s_waitcnt lgkmcnt(0)
	v_mfma_f32_16x16x32_bf16 v[124:127], v[128:131], v[144:147], v[124:127]
	v_mfma_f32_16x16x32_bf16 v[120:123], v[136:139], v[144:147], v[120:123]
	v_mfma_f32_16x16x32_bf16 v[108:111], v[128:131], v[152:155], v[108:111]
	v_mfma_f32_16x16x32_bf16 v[104:107], v[136:139], v[152:155], v[104:107]
	v_mfma_f32_16x16x32_bf16 v[92:95], v[128:131], v[160:163], v[92:95]
	v_mfma_f32_16x16x32_bf16 v[88:91], v[136:139], v[160:163], v[88:91]
	v_mfma_f32_16x16x32_bf16 v[76:79], v[128:131], v[168:171], v[76:79]
	v_mfma_f32_16x16x32_bf16 v[72:75], v[136:139], v[168:171], v[72:75]
	v_mfma_f32_16x16x32_bf16 v[124:127], v[132:135], v[148:151], v[124:127]
	v_mfma_f32_16x16x32_bf16 v[120:123], v[140:143], v[148:151], v[120:123]
	v_mfma_f32_16x16x32_bf16 v[108:111], v[132:135], v[156:159], v[108:111]
	v_mfma_f32_16x16x32_bf16 v[104:107], v[140:143], v[156:159], v[104:107]
	v_mfma_f32_16x16x32_bf16 v[92:95], v[132:135], v[164:167], v[92:95]
	v_mfma_f32_16x16x32_bf16 v[88:91], v[140:143], v[164:167], v[88:91]
	v_mfma_f32_16x16x32_bf16 v[76:79], v[132:135], v[172:175], v[76:79]
	v_mfma_f32_16x16x32_bf16 v[72:75], v[140:143], v[172:175], v[72:75]
	s_barrier
	s_add_i32 s26, 0, 0x1c000
	s_add_i32 s20, s46, s31
	s_add_u32 s100, s24, 0x80
	s_addc_u32 s101, s25, 0
	s_mov_b32 m0, s20
	ds_read_b128 v[176:179], v219
	ds_read_b128 v[180:183], v219 offset:1024
	ds_read_b128 v[184:187], v219 offset:2048
	ds_read_b128 v[188:191], v219 offset:3072
	global_load_lds_dwordx4 v192, s[100:101]
	s_add_i32 m0, s20, 0x2000
	s_nop 0
	global_load_lds_dwordx4 v210, s[100:101]
	s_barrier
	s_waitcnt lgkmcnt(0)
	v_mfma_f32_16x16x32_bf16 v[116:119], v[176:179], v[144:147], v[116:119]
	v_mfma_f32_16x16x32_bf16 v[112:115], v[184:187], v[144:147], v[112:115]
	v_mfma_f32_16x16x32_bf16 v[100:103], v[176:179], v[152:155], v[100:103]
	v_mfma_f32_16x16x32_bf16 v[96:99], v[184:187], v[152:155], v[96:99]
	v_mfma_f32_16x16x32_bf16 v[84:87], v[176:179], v[160:163], v[84:87]
	v_mfma_f32_16x16x32_bf16 v[80:83], v[184:187], v[160:163], v[80:83]
	v_mfma_f32_16x16x32_bf16 v[68:71], v[176:179], v[168:171], v[68:71]
	v_mfma_f32_16x16x32_bf16 v[64:67], v[184:187], v[168:171], v[64:67]
	v_mfma_f32_16x16x32_bf16 v[116:119], v[180:183], v[148:151], v[116:119]
	v_mfma_f32_16x16x32_bf16 v[112:115], v[188:191], v[148:151], v[112:115]
	v_mfma_f32_16x16x32_bf16 v[100:103], v[180:183], v[156:159], v[100:103]
	v_mfma_f32_16x16x32_bf16 v[96:99], v[188:191], v[156:159], v[96:99]
	v_mfma_f32_16x16x32_bf16 v[84:87], v[180:183], v[164:167], v[84:87]
	v_mfma_f32_16x16x32_bf16 v[80:83], v[188:191], v[164:167], v[80:83]
	v_mfma_f32_16x16x32_bf16 v[68:71], v[180:183], v[172:175], v[68:71]
	v_mfma_f32_16x16x32_bf16 v[64:67], v[188:191], v[172:175], v[64:67]
	s_mov_b32 m0, s38
	s_barrier
	ds_read_b128 v[144:147], v198 offset:49152
	ds_read_b128 v[148:151], v198 offset:50176
	ds_read_b128 v[152:155], v198 offset:51200
	ds_read_b128 v[156:159], v198 offset:52224
	ds_read_b128 v[160:163], v198 offset:53248
	ds_read_b128 v[164:167], v198 offset:54272
	ds_read_b128 v[168:171], v198 offset:55296
	ds_read_b128 v[172:175], v198 offset:56320
	global_load_lds_dwordx4 v206, vcc
	s_mov_b32 m0, s39
	s_nop 0
	global_load_lds_dwordx4 v208, vcc
	s_barrier
	s_waitcnt lgkmcnt(0)
	v_mfma_f32_16x16x32_bf16 v[60:63], v[128:131], v[144:147], v[60:63]
	v_mfma_f32_16x16x32_bf16 v[56:59], v[136:139], v[144:147], v[56:59]
	v_mfma_f32_16x16x32_bf16 v[44:47], v[128:131], v[152:155], v[44:47]
	v_mfma_f32_16x16x32_bf16 v[40:43], v[136:139], v[152:155], v[40:43]
	v_mfma_f32_16x16x32_bf16 v[28:31], v[128:131], v[160:163], v[28:31]
	v_mfma_f32_16x16x32_bf16 v[24:27], v[136:139], v[160:163], v[24:27]
	v_mfma_f32_16x16x32_bf16 v[12:15], v[128:131], v[168:171], v[12:15]
	v_mfma_f32_16x16x32_bf16 v[8:11], v[136:139], v[168:171], v[8:11]
	v_mfma_f32_16x16x32_bf16 v[60:63], v[132:135], v[148:151], v[60:63]
	v_mfma_f32_16x16x32_bf16 v[56:59], v[140:143], v[148:151], v[56:59]
	v_mfma_f32_16x16x32_bf16 v[44:47], v[132:135], v[156:159], v[44:47]
	v_mfma_f32_16x16x32_bf16 v[40:43], v[140:143], v[156:159], v[40:43]
	v_mfma_f32_16x16x32_bf16 v[28:31], v[132:135], v[164:167], v[28:31]
	v_mfma_f32_16x16x32_bf16 v[24:27], v[140:143], v[164:167], v[24:27]
	v_mfma_f32_16x16x32_bf16 v[12:15], v[132:135], v[172:175], v[12:15]
	v_mfma_f32_16x16x32_bf16 v[8:11], v[140:143], v[172:175], v[8:11]
	s_barrier
	s_add_u32 s20, s24, 0xb0080
	s_addc_u32 s21, s25, 0
	s_add_i32 s24, s26, s31
	s_mov_b32 m0, s24
	s_nop 0
	global_load_lds_dwordx4 v192, s[20:21]
	s_add_i32 m0, s24, 0x2000
	s_nop 0
	global_load_lds_dwordx4 v210, s[20:21]
	s_waitcnt vmcnt(6)
	s_barrier
	v_mfma_f32_16x16x32_bf16 v[52:55], v[176:179], v[144:147], v[52:55]
	v_mfma_f32_16x16x32_bf16 v[48:51], v[184:187], v[144:147], v[48:51]
	v_mfma_f32_16x16x32_bf16 v[36:39], v[176:179], v[152:155], v[36:39]
	v_mfma_f32_16x16x32_bf16 v[32:35], v[184:187], v[152:155], v[32:35]
	v_mfma_f32_16x16x32_bf16 v[20:23], v[176:179], v[160:163], v[20:23]
	v_mfma_f32_16x16x32_bf16 v[16:19], v[184:187], v[160:163], v[16:19]
	v_mfma_f32_16x16x32_bf16 v[4:7], v[176:179], v[168:171], v[4:7]
	v_mfma_f32_16x16x32_bf16 v[0:3], v[184:187], v[168:171], v[0:3]
	v_mfma_f32_16x16x32_bf16 v[52:55], v[180:183], v[148:151], v[52:55]
	v_mfma_f32_16x16x32_bf16 v[48:51], v[188:191], v[148:151], v[48:51]
	v_mfma_f32_16x16x32_bf16 v[36:39], v[180:183], v[156:159], v[36:39]
	v_mfma_f32_16x16x32_bf16 v[32:35], v[188:191], v[156:159], v[32:35]
	v_mfma_f32_16x16x32_bf16 v[20:23], v[180:183], v[164:167], v[20:23]
	v_mfma_f32_16x16x32_bf16 v[16:19], v[188:191], v[164:167], v[16:19]
	v_mfma_f32_16x16x32_bf16 v[4:7], v[180:183], v[172:175], v[4:7]
	v_mfma_f32_16x16x32_bf16 v[0:3], v[188:191], v[172:175], v[0:3]
	s_add_i32 s45, s45, 2
	s_add_u32 s33, s33, 0x100
	s_addc_u32 s44, s44, 0
	s_cmp_gt_u32 s45, 41
	s_mov_b64 s[20:21], s[22:23]
	s_barrier

.LBB0_2147:
	v_mov_b64_e32 v[0:1], 0x80
	s_ashr_i32 s19, s18, 31
	v_cmp_lt_i64_e32 vcc, s[26:27], v[0:1]
	s_lshl_b64 s[0:1], s[18:19], 19
	v_readlane_b32 s26, v254, 33
	v_readlane_b32 s27, v254, 34
	s_add_u32 s26, s26, s0
	s_addc_u32 s27, s27, s1
	s_and_b64 s[0:1], vcc, exec
	s_cselect_b32 s0, s27, s31
	s_cselect_b32 s1, s26, s30
	s_ashr_i32 s25, s24, 31
	s_lshl_b64 s[28:29], s[24:25], 19
	s_add_u32 s28, s41, s28
	s_addc_u32 s29, s42, s29
	s_and_b64 s[36:37], vcc, exec
	s_cselect_b32 s7, s29, s35
	s_cselect_b32 s9, s28, s34
	s_add_u32 s30, s30, 0x40080
	s_addc_u32 s31, s31, 0
	s_add_u32 s19, s34, 0x100
	s_addc_u32 s25, s35, 0
	s_mov_b32 s33, -2
	s_waitcnt vmcnt(0)
	s_add_u32 s34, s30, 0xfffc0080
	s_addc_u32 s35, s31, -1
	s_add_i32 s51, 0, 0x10000
	v_add_u32_e32 v146, s51, v148
	ds_read_b128 v[138:141], v146
	ds_read_b128 v[142:145], v146 offset:1024
	ds_read_b128 v[150:153], v146 offset:2048
	ds_read_b128 v[154:157], v146 offset:3072
	s_cmp_eq_u32 s33, 12
	s_cselect_b32 s37, s0, s35
	s_cselect_b32 s36, s1, s34
	s_cselect_b32 s35, s7, s25
	s_cselect_b32 s34, s9, s19
	s_add_i32 m0, s44, 0xc000
	ds_read_b128 v[158:161], v149
	ds_read_b128 v[162:165], v149 offset:1024
	ds_read_b128 v[166:169], v149 offset:2048
	ds_read_b128 v[170:173], v149 offset:3072
	ds_read_b128 v[174:177], v149 offset:4096
	ds_read_b128 v[178:181], v149 offset:5120
	ds_read_b128 v[182:185], v149 offset:6144
	ds_read_b128 v[186:189], v149 offset:7168
	global_load_lds_dwordx4 v134, s[30:31]
	s_add_i32 m0, s44, 0xe000
	s_nop 0
	global_load_lds_dwordx4 v136, s[30:31]
	s_waitcnt lgkmcnt(8)
	s_barrier
	s_waitcnt lgkmcnt(0)
	v_mfma_f32_16x16x32_bf16 v[124:127], v[138:141], v[158:161], 0
	v_mfma_f32_16x16x32_bf16 v[120:123], v[150:153], v[158:161], 0
	v_mfma_f32_16x16x32_bf16 v[108:111], v[138:141], v[166:169], 0
	v_mfma_f32_16x16x32_bf16 v[104:107], v[150:153], v[166:169], 0
	v_mfma_f32_16x16x32_bf16 v[92:95], v[138:141], v[174:177], 0
	v_mfma_f32_16x16x32_bf16 v[88:91], v[150:153], v[174:177], 0
	v_mfma_f32_16x16x32_bf16 v[76:79], v[138:141], v[182:185], 0
	v_mfma_f32_16x16x32_bf16 v[72:75], v[150:153], v[182:185], 0
	v_mfma_f32_16x16x32_bf16 v[124:127], v[142:145], v[162:165], v[124:127]
	v_mfma_f32_16x16x32_bf16 v[120:123], v[154:157], v[162:165], v[120:123]
	v_mfma_f32_16x16x32_bf16 v[108:111], v[142:145], v[170:173], v[108:111]
	v_mfma_f32_16x16x32_bf16 v[104:107], v[154:157], v[170:173], v[104:107]
	v_mfma_f32_16x16x32_bf16 v[92:95], v[142:145], v[178:181], v[92:95]
	v_mfma_f32_16x16x32_bf16 v[88:91], v[154:157], v[178:181], v[88:91]
	v_mfma_f32_16x16x32_bf16 v[76:79], v[142:145], v[186:189], v[76:79]
	v_mfma_f32_16x16x32_bf16 v[72:75], v[154:157], v[186:189], v[72:75]
	s_barrier
	s_add_i32 s54, 0, 0x14000
	v_add_u32_e32 v146, s54, v148
	s_add_i32 s51, s51, s43
	ds_read_b128 v[198:201], v146
	ds_read_b128 v[206:209], v146 offset:1024
	ds_read_b128 v[210:213], v146 offset:2048
	ds_read_b128 v[214:217], v146 offset:3072
	s_mov_b32 m0, s51
	s_nop 0
	global_load_lds_dwordx4 v192, s[34:35]
	s_add_i32 m0, s51, 0x2000
	s_nop 0
	global_load_lds_dwordx4 v132, s[34:35]
	s_barrier
	s_waitcnt lgkmcnt(0)
	v_mfma_f32_16x16x32_bf16 v[116:119], v[198:201], v[158:161], 0
	v_mfma_f32_16x16x32_bf16 v[112:115], v[210:213], v[158:161], 0
	v_mfma_f32_16x16x32_bf16 v[100:103], v[198:201], v[166:169], 0
	v_mfma_f32_16x16x32_bf16 v[96:99], v[210:213], v[166:169], 0
	v_mfma_f32_16x16x32_bf16 v[84:87], v[198:201], v[174:177], 0
	v_mfma_f32_16x16x32_bf16 v[80:83], v[210:213], v[174:177], 0
	v_mfma_f32_16x16x32_bf16 v[68:71], v[198:201], v[182:185], 0
	v_mfma_f32_16x16x32_bf16 v[64:67], v[210:213], v[182:185], 0
	v_mfma_f32_16x16x32_bf16 v[116:119], v[206:209], v[162:165], v[116:119]
	v_mfma_f32_16x16x32_bf16 v[112:115], v[214:217], v[162:165], v[112:115]
	v_mfma_f32_16x16x32_bf16 v[100:103], v[206:209], v[170:173], v[100:103]
	v_mfma_f32_16x16x32_bf16 v[96:99], v[214:217], v[170:173], v[96:99]
	v_mfma_f32_16x16x32_bf16 v[84:87], v[206:209], v[178:181], v[84:87]
	v_mfma_f32_16x16x32_bf16 v[80:83], v[214:217], v[178:181], v[80:83]
	v_mfma_f32_16x16x32_bf16 v[68:71], v[206:209], v[186:189], v[68:71]
	v_mfma_f32_16x16x32_bf16 v[64:67], v[214:217], v[186:189], v[64:67]
	s_mov_b32 m0, s44
	s_add_u32 vcc_lo, s36, 0x80
	s_addc_u32 vcc_hi, s37, 0
	s_barrier
	ds_read_b128 v[158:161], v149 offset:16384
	ds_read_b128 v[162:165], v149 offset:17408
	ds_read_b128 v[166:169], v149 offset:18432
	ds_read_b128 v[170:173], v149 offset:19456
	ds_read_b128 v[174:177], v149 offset:20480
	ds_read_b128 v[178:181], v149 offset:21504
	ds_read_b128 v[182:185], v149 offset:22528
	ds_read_b128 v[186:189], v149 offset:23552
	global_load_lds_dwordx4 v128, s[36:37]
	s_mov_b32 m0, s45
	s_nop 0
	global_load_lds_dwordx4 v130, s[36:37]
	s_barrier
	s_waitcnt lgkmcnt(0)
	v_mfma_f32_16x16x32_bf16 v[60:63], v[138:141], v[158:161], 0
	v_mfma_f32_16x16x32_bf16 v[56:59], v[150:153], v[158:161], 0
	v_mfma_f32_16x16x32_bf16 v[44:47], v[138:141], v[166:169], 0
	v_mfma_f32_16x16x32_bf16 v[40:43], v[150:153], v[166:169], 0
	v_mfma_f32_16x16x32_bf16 v[28:31], v[138:141], v[174:177], 0
	v_mfma_f32_16x16x32_bf16 v[24:27], v[150:153], v[174:177], 0
	v_mfma_f32_16x16x32_bf16 v[12:15], v[138:141], v[182:185], 0
	v_mfma_f32_16x16x32_bf16 v[8:11], v[150:153], v[182:185], 0
	v_mfma_f32_16x16x32_bf16 v[60:63], v[142:145], v[162:165], v[60:63]
	v_mfma_f32_16x16x32_bf16 v[56:59], v[154:157], v[162:165], v[56:59]
	v_mfma_f32_16x16x32_bf16 v[44:47], v[142:145], v[170:173], v[44:47]
	v_mfma_f32_16x16x32_bf16 v[40:43], v[154:157], v[170:173], v[40:43]
	v_mfma_f32_16x16x32_bf16 v[28:31], v[142:145], v[178:181], v[28:31]
	v_mfma_f32_16x16x32_bf16 v[24:27], v[154:157], v[178:181], v[24:27]
	v_mfma_f32_16x16x32_bf16 v[12:15], v[142:145], v[186:189], v[12:15]
	v_mfma_f32_16x16x32_bf16 v[8:11], v[154:157], v[186:189], v[8:11]
	s_barrier
	s_add_u32 s52, s34, 0x40000
	s_addc_u32 s53, s35, 0
	s_add_i32 s51, s54, s43
	s_mov_b32 m0, s51
	s_nop 0
	global_load_lds_dwordx4 v192, s[52:53]
	s_add_i32 m0, s51, 0x2000
	s_nop 0
	global_load_lds_dwordx4 v132, s[52:53]
	s_waitcnt vmcnt(6)
	s_barrier
	v_mfma_f32_16x16x32_bf16 v[52:55], v[198:201], v[158:161], 0
	v_mfma_f32_16x16x32_bf16 v[48:51], v[210:213], v[158:161], 0
	v_mfma_f32_16x16x32_bf16 v[36:39], v[198:201], v[166:169], 0
	v_mfma_f32_16x16x32_bf16 v[32:35], v[210:213], v[166:169], 0
	v_mfma_f32_16x16x32_bf16 v[20:23], v[198:201], v[174:177], 0
	v_mfma_f32_16x16x32_bf16 v[16:19], v[210:213], v[174:177], 0
	v_mfma_f32_16x16x32_bf16 v[4:7], v[198:201], v[182:185], 0
	v_mfma_f32_16x16x32_bf16 v[0:3], v[210:213], v[182:185], 0
	v_mfma_f32_16x16x32_bf16 v[52:55], v[206:209], v[162:165], v[52:55]
	v_mfma_f32_16x16x32_bf16 v[48:51], v[214:217], v[162:165], v[48:51]
	v_mfma_f32_16x16x32_bf16 v[36:39], v[206:209], v[170:173], v[36:39]
	v_mfma_f32_16x16x32_bf16 v[32:35], v[214:217], v[170:173], v[32:35]
	v_mfma_f32_16x16x32_bf16 v[20:23], v[206:209], v[178:181], v[20:23]
	v_mfma_f32_16x16x32_bf16 v[16:19], v[214:217], v[178:181], v[16:19]
	v_mfma_f32_16x16x32_bf16 v[4:7], v[206:209], v[186:189], v[4:7]
	v_mfma_f32_16x16x32_bf16 v[0:3], v[214:217], v[186:189], v[0:3]
	s_add_i32 s51, 0, 0x18000
	v_add_u32_e32 v154, s51, v148
	s_barrier
	ds_read_b128 v[138:141], v154
	ds_read_b128 v[142:145], v154 offset:1024
	ds_read_b128 v[150:153], v154 offset:2048
	ds_read_b128 v[154:157], v154 offset:3072
	s_add_u32 s36, s36, 0x40000
	s_addc_u32 s37, s37, 0
	s_mov_b32 m0, s46
	ds_read_b128 v[158:161], v149 offset:32768
	ds_read_b128 v[162:165], v149 offset:33792
	ds_read_b128 v[166:169], v149 offset:34816
	ds_read_b128 v[170:173], v149 offset:35840
	ds_read_b128 v[174:177], v149 offset:36864
	ds_read_b128 v[178:181], v149 offset:37888
	ds_read_b128 v[182:185], v149 offset:38912
	ds_read_b128 v[186:189], v149 offset:39936
	global_load_lds_dwordx4 v128, s[36:37]
	s_mov_b32 m0, s47
	s_nop 0
	global_load_lds_dwordx4 v130, s[36:37]
	s_waitcnt lgkmcnt(8)
	s_barrier
	s_waitcnt lgkmcnt(0)
	v_mfma_f32_16x16x32_bf16 v[124:127], v[138:141], v[158:161], v[124:127]
	v_mfma_f32_16x16x32_bf16 v[120:123], v[150:153], v[158:161], v[120:123]
	v_mfma_f32_16x16x32_bf16 v[108:111], v[138:141], v[166:169], v[108:111]
	v_mfma_f32_16x16x32_bf16 v[104:107], v[150:153], v[166:169], v[104:107]
	v_mfma_f32_16x16x32_bf16 v[92:95], v[138:141], v[174:177], v[92:95]
	v_mfma_f32_16x16x32_bf16 v[88:91], v[150:153], v[174:177], v[88:91]
	v_mfma_f32_16x16x32_bf16 v[76:79], v[138:141], v[182:185], v[76:79]
	v_mfma_f32_16x16x32_bf16 v[72:75], v[150:153], v[182:185], v[72:75]
	v_mfma_f32_16x16x32_bf16 v[124:127], v[142:145], v[162:165], v[124:127]
	v_mfma_f32_16x16x32_bf16 v[120:123], v[154:157], v[162:165], v[120:123]
	v_mfma_f32_16x16x32_bf16 v[108:111], v[142:145], v[170:173], v[108:111]
	v_mfma_f32_16x16x32_bf16 v[104:107], v[154:157], v[170:173], v[104:107]
	v_mfma_f32_16x16x32_bf16 v[92:95], v[142:145], v[178:181], v[92:95]
	v_mfma_f32_16x16x32_bf16 v[88:91], v[154:157], v[178:181], v[88:91]
	v_mfma_f32_16x16x32_bf16 v[76:79], v[142:145], v[186:189], v[76:79]
	v_mfma_f32_16x16x32_bf16 v[72:75], v[154:157], v[186:189], v[72:75]
	s_barrier
	s_add_i32 s36, 0, 0x1c000
	s_add_i32 s37, s51, s43
	v_add_u32_e32 v196, s36, v148
	s_add_u32 s100, s34, 0x80
	s_addc_u32 s101, s35, 0
	s_mov_b32 m0, s37
	ds_read_b128 v[198:201], v196
	ds_read_b128 v[206:209], v196 offset:1024
	ds_read_b128 v[210:213], v196 offset:2048
	ds_read_b128 v[214:217], v196 offset:3072
	global_load_lds_dwordx4 v192, s[100:101]
	s_add_i32 m0, s37, 0x2000
	s_nop 0
	global_load_lds_dwordx4 v132, s[100:101]
	s_barrier
	s_waitcnt lgkmcnt(0)
	v_mfma_f32_16x16x32_bf16 v[116:119], v[198:201], v[158:161], v[116:119]
	v_mfma_f32_16x16x32_bf16 v[112:115], v[210:213], v[158:161], v[112:115]
	v_mfma_f32_16x16x32_bf16 v[100:103], v[198:201], v[166:169], v[100:103]
	v_mfma_f32_16x16x32_bf16 v[96:99], v[210:213], v[166:169], v[96:99]
	v_mfma_f32_16x16x32_bf16 v[84:87], v[198:201], v[174:177], v[84:87]
	v_mfma_f32_16x16x32_bf16 v[80:83], v[210:213], v[174:177], v[80:83]
	v_mfma_f32_16x16x32_bf16 v[68:71], v[198:201], v[182:185], v[68:71]
	v_mfma_f32_16x16x32_bf16 v[64:67], v[210:213], v[182:185], v[64:67]
	v_mfma_f32_16x16x32_bf16 v[116:119], v[206:209], v[162:165], v[116:119]
	v_mfma_f32_16x16x32_bf16 v[112:115], v[214:217], v[162:165], v[112:115]
	v_mfma_f32_16x16x32_bf16 v[100:103], v[206:209], v[170:173], v[100:103]
	v_mfma_f32_16x16x32_bf16 v[96:99], v[214:217], v[170:173], v[96:99]
	v_mfma_f32_16x16x32_bf16 v[84:87], v[206:209], v[178:181], v[84:87]
	v_mfma_f32_16x16x32_bf16 v[80:83], v[214:217], v[178:181], v[80:83]
	v_mfma_f32_16x16x32_bf16 v[68:71], v[206:209], v[186:189], v[68:71]
	v_mfma_f32_16x16x32_bf16 v[64:67], v[214:217], v[186:189], v[64:67]
	s_mov_b32 m0, s48
	s_barrier
	ds_read_b128 v[158:161], v149 offset:49152
	ds_read_b128 v[162:165], v149 offset:50176
	ds_read_b128 v[166:169], v149 offset:51200
	ds_read_b128 v[170:173], v149 offset:52224
	ds_read_b128 v[174:177], v149 offset:53248
	ds_read_b128 v[178:181], v149 offset:54272
	ds_read_b128 v[182:185], v149 offset:55296
	ds_read_b128 v[186:189], v149 offset:56320
	global_load_lds_dwordx4 v128, vcc
	s_mov_b32 m0, s49
	s_nop 0
	global_load_lds_dwordx4 v130, vcc
	s_barrier
	s_waitcnt lgkmcnt(0)
	v_mfma_f32_16x16x32_bf16 v[60:63], v[138:141], v[158:161], v[60:63]
	v_mfma_f32_16x16x32_bf16 v[56:59], v[150:153], v[158:161], v[56:59]
	v_mfma_f32_16x16x32_bf16 v[44:47], v[138:141], v[166:169], v[44:47]
	v_mfma_f32_16x16x32_bf16 v[40:43], v[150:153], v[166:169], v[40:43]
	v_mfma_f32_16x16x32_bf16 v[28:31], v[138:141], v[174:177], v[28:31]
	v_mfma_f32_16x16x32_bf16 v[24:27], v[150:153], v[174:177], v[24:27]
	v_mfma_f32_16x16x32_bf16 v[12:15], v[138:141], v[182:185], v[12:15]
	v_mfma_f32_16x16x32_bf16 v[8:11], v[150:153], v[182:185], v[8:11]
	v_mfma_f32_16x16x32_bf16 v[60:63], v[142:145], v[162:165], v[60:63]
	v_mfma_f32_16x16x32_bf16 v[56:59], v[154:157], v[162:165], v[56:59]
	v_mfma_f32_16x16x32_bf16 v[44:47], v[142:145], v[170:173], v[44:47]
	v_mfma_f32_16x16x32_bf16 v[40:43], v[154:157], v[170:173], v[40:43]
	v_mfma_f32_16x16x32_bf16 v[28:31], v[142:145], v[178:181], v[28:31]
	v_mfma_f32_16x16x32_bf16 v[24:27], v[154:157], v[178:181], v[24:27]
	v_mfma_f32_16x16x32_bf16 v[12:15], v[142:145], v[186:189], v[12:15]
	v_mfma_f32_16x16x32_bf16 v[8:11], v[154:157], v[186:189], v[8:11]
	s_barrier
	s_add_u32 s34, s34, 0x40080
	s_addc_u32 s35, s35, 0
	s_add_i32 s36, s36, s43
	s_mov_b32 m0, s36
	s_nop 0
	global_load_lds_dwordx4 v192, s[34:35]
	s_add_i32 m0, s36, 0x2000
	s_nop 0
	global_load_lds_dwordx4 v132, s[34:35]
	s_waitcnt vmcnt(6)
	s_barrier
	v_mfma_f32_16x16x32_bf16 v[52:55], v[198:201], v[158:161], v[52:55]
	v_mfma_f32_16x16x32_bf16 v[48:51], v[210:213], v[158:161], v[48:51]
	v_mfma_f32_16x16x32_bf16 v[36:39], v[198:201], v[166:169], v[36:39]
	v_mfma_f32_16x16x32_bf16 v[32:35], v[210:213], v[166:169], v[32:35]
	v_mfma_f32_16x16x32_bf16 v[20:23], v[198:201], v[174:177], v[20:23]
	v_mfma_f32_16x16x32_bf16 v[16:19], v[210:213], v[174:177], v[16:19]
	v_mfma_f32_16x16x32_bf16 v[4:7], v[198:201], v[182:185], v[4:7]
	v_mfma_f32_16x16x32_bf16 v[0:3], v[210:213], v[182:185], v[0:3]
	v_mfma_f32_16x16x32_bf16 v[52:55], v[206:209], v[162:165], v[52:55]
	v_mfma_f32_16x16x32_bf16 v[48:51], v[214:217], v[162:165], v[48:51]
	v_mfma_f32_16x16x32_bf16 v[36:39], v[206:209], v[170:173], v[36:39]
	v_mfma_f32_16x16x32_bf16 v[32:35], v[214:217], v[170:173], v[32:35]
	v_mfma_f32_16x16x32_bf16 v[20:23], v[206:209], v[178:181], v[20:23]
	v_mfma_f32_16x16x32_bf16 v[16:19], v[214:217], v[178:181], v[16:19]
	v_mfma_f32_16x16x32_bf16 v[4:7], v[206:209], v[186:189], v[4:7]
	v_mfma_f32_16x16x32_bf16 v[0:3], v[214:217], v[186:189], v[0:3]
	s_add_i32 s33, s33, 2
	s_add_u32 s30, s30, 0x100
	s_addc_u32 s31, s31, 0
	s_add_u32 s19, s19, 0x100
	s_addc_u32 s25, s25, 0
	s_cmp_gt_u32 s33, 13
	s_barrier

.LBB0_2291:
	s_add_u32 s33, s14, 0x100
	s_addc_u32 s51, s15, 0
	s_mov_b32 s52, -2
	s_waitcnt vmcnt(0)
	s_add_u32 s8, s12, 0x100
	s_addc_u32 s9, s13, 0
	s_add_i32 s53, 0, 0x10000
	v_add_u32_e32 v140, s53, v196
	ds_read_b128 v[128:131], v140
	ds_read_b128 v[132:135], v140 offset:1024
	ds_read_b128 v[136:139], v140 offset:2048
	ds_read_b128 v[140:143], v140 offset:3072
	s_cmp_eq_u32 s52, 2
	s_cselect_b32 s15, s31, s9
	s_cselect_b32 s14, s30, s8
	s_cselect_b32 s11, s35, s51
	s_cselect_b32 s10, s34, s33
	s_add_i32 m0, s42, 0xc000
	ds_read_b128 v[144:147], v198
	ds_read_b128 v[148:151], v198 offset:1024
	ds_read_b128 v[152:155], v198 offset:2048
	ds_read_b128 v[156:159], v198 offset:3072
	ds_read_b128 v[160:163], v198 offset:4096
	ds_read_b128 v[164:167], v198 offset:5120
	ds_read_b128 v[168:171], v198 offset:6144
	ds_read_b128 v[172:175], v198 offset:7168
	global_load_lds_dwordx4 v190, s[12:13]
	s_add_i32 m0, s42, 0xe000
	s_nop 0
	global_load_lds_dwordx4 v206, s[12:13]
	s_waitcnt lgkmcnt(8)
	s_barrier
	s_waitcnt lgkmcnt(0)
	v_mfma_f32_16x16x32_bf16 v[124:127], v[128:131], v[144:147], 0
	v_mfma_f32_16x16x32_bf16 v[120:123], v[136:139], v[144:147], 0
	v_mfma_f32_16x16x32_bf16 v[108:111], v[128:131], v[152:155], 0
	v_mfma_f32_16x16x32_bf16 v[104:107], v[136:139], v[152:155], 0
	v_mfma_f32_16x16x32_bf16 v[92:95], v[128:131], v[160:163], 0
	v_mfma_f32_16x16x32_bf16 v[88:91], v[136:139], v[160:163], 0
	v_mfma_f32_16x16x32_bf16 v[76:79], v[128:131], v[168:171], 0
	v_mfma_f32_16x16x32_bf16 v[72:75], v[136:139], v[168:171], 0
	v_mfma_f32_16x16x32_bf16 v[124:127], v[132:135], v[148:151], v[124:127]
	v_mfma_f32_16x16x32_bf16 v[120:123], v[140:143], v[148:151], v[120:123]
	v_mfma_f32_16x16x32_bf16 v[108:111], v[132:135], v[156:159], v[108:111]
	v_mfma_f32_16x16x32_bf16 v[104:107], v[140:143], v[156:159], v[104:107]
	v_mfma_f32_16x16x32_bf16 v[92:95], v[132:135], v[164:167], v[92:95]
	v_mfma_f32_16x16x32_bf16 v[88:91], v[140:143], v[164:167], v[88:91]
	v_mfma_f32_16x16x32_bf16 v[76:79], v[132:135], v[172:175], v[76:79]
	v_mfma_f32_16x16x32_bf16 v[72:75], v[140:143], v[172:175], v[72:75]
	s_barrier
	s_add_i32 s54, 0, 0x14000
	v_add_u32_e32 v184, s54, v196
	s_add_i32 s12, s53, s41
	ds_read_b128 v[176:179], v184
	ds_read_b128 v[180:183], v184 offset:1024
	ds_read_b128 v[208:211], v184 offset:2048
	ds_read_b128 v[212:215], v184 offset:3072
	s_mov_b32 m0, s12
	s_nop 0
	global_load_lds_dwordx4 v186, s[10:11]
	s_add_i32 m0, s12, 0x2000
	s_nop 0
	global_load_lds_dwordx4 v188, s[10:11]
	s_barrier
	s_waitcnt lgkmcnt(0)
	v_mfma_f32_16x16x32_bf16 v[116:119], v[176:179], v[144:147], 0
	v_mfma_f32_16x16x32_bf16 v[112:115], v[208:211], v[144:147], 0
	v_mfma_f32_16x16x32_bf16 v[100:103], v[176:179], v[152:155], 0
	v_mfma_f32_16x16x32_bf16 v[96:99], v[208:211], v[152:155], 0
	v_mfma_f32_16x16x32_bf16 v[84:87], v[176:179], v[160:163], 0
	v_mfma_f32_16x16x32_bf16 v[80:83], v[208:211], v[160:163], 0
	v_mfma_f32_16x16x32_bf16 v[68:71], v[176:179], v[168:171], 0
	v_mfma_f32_16x16x32_bf16 v[64:67], v[208:211], v[168:171], 0
	v_mfma_f32_16x16x32_bf16 v[116:119], v[180:183], v[148:151], v[116:119]
	v_mfma_f32_16x16x32_bf16 v[112:115], v[212:215], v[148:151], v[112:115]
	v_mfma_f32_16x16x32_bf16 v[100:103], v[180:183], v[156:159], v[100:103]
	v_mfma_f32_16x16x32_bf16 v[96:99], v[212:215], v[156:159], v[96:99]
	v_mfma_f32_16x16x32_bf16 v[84:87], v[180:183], v[164:167], v[84:87]
	v_mfma_f32_16x16x32_bf16 v[80:83], v[212:215], v[164:167], v[80:83]
	v_mfma_f32_16x16x32_bf16 v[68:71], v[180:183], v[172:175], v[68:71]
	v_mfma_f32_16x16x32_bf16 v[64:67], v[212:215], v[172:175], v[64:67]
	s_mov_b32 m0, s42
	s_barrier
	ds_read_b128 v[144:147], v198 offset:16384
	ds_read_b128 v[148:151], v198 offset:17408
	ds_read_b128 v[152:155], v198 offset:18432
	ds_read_b128 v[156:159], v198 offset:19456
	ds_read_b128 v[160:163], v198 offset:20480
	ds_read_b128 v[164:167], v198 offset:21504
	ds_read_b128 v[168:171], v198 offset:22528
	ds_read_b128 v[172:175], v198 offset:23552
	global_load_lds_dwordx4 v186, s[14:15]
	s_mov_b32 m0, s43
	s_nop 0
	global_load_lds_dwordx4 v188, s[14:15]
	s_barrier
	s_waitcnt lgkmcnt(0)
	v_mfma_f32_16x16x32_bf16 v[60:63], v[128:131], v[144:147], 0
	v_mfma_f32_16x16x32_bf16 v[56:59], v[136:139], v[144:147], 0
	v_mfma_f32_16x16x32_bf16 v[44:47], v[128:131], v[152:155], 0
	v_mfma_f32_16x16x32_bf16 v[40:43], v[136:139], v[152:155], 0
	v_mfma_f32_16x16x32_bf16 v[28:31], v[128:131], v[160:163], 0
	v_mfma_f32_16x16x32_bf16 v[24:27], v[136:139], v[160:163], 0
	v_mfma_f32_16x16x32_bf16 v[12:15], v[128:131], v[168:171], 0
	v_mfma_f32_16x16x32_bf16 v[8:11], v[136:139], v[168:171], 0
	v_mfma_f32_16x16x32_bf16 v[60:63], v[132:135], v[148:151], v[60:63]
	v_mfma_f32_16x16x32_bf16 v[56:59], v[140:143], v[148:151], v[56:59]
	v_mfma_f32_16x16x32_bf16 v[44:47], v[132:135], v[156:159], v[44:47]
	v_mfma_f32_16x16x32_bf16 v[40:43], v[140:143], v[156:159], v[40:43]
	v_mfma_f32_16x16x32_bf16 v[28:31], v[132:135], v[164:167], v[28:31]
	v_mfma_f32_16x16x32_bf16 v[24:27], v[140:143], v[164:167], v[24:27]
	v_mfma_f32_16x16x32_bf16 v[12:15], v[132:135], v[172:175], v[12:15]
	v_mfma_f32_16x16x32_bf16 v[8:11], v[140:143], v[172:175], v[8:11]
	s_barrier
	s_add_u32 s12, s10, 0x18000
	s_addc_u32 s13, s11, 0
	s_add_i32 s53, s54, s41
	s_mov_b32 m0, s53
	s_nop 0
	global_load_lds_dwordx4 v186, s[12:13]
	s_add_i32 m0, s53, 0x2000
	s_nop 0
	global_load_lds_dwordx4 v188, s[12:13]
	s_waitcnt vmcnt(6)
	s_barrier
	v_mfma_f32_16x16x32_bf16 v[52:55], v[176:179], v[144:147], 0
	v_mfma_f32_16x16x32_bf16 v[48:51], v[208:211], v[144:147], 0
	v_mfma_f32_16x16x32_bf16 v[36:39], v[176:179], v[152:155], 0
	v_mfma_f32_16x16x32_bf16 v[32:35], v[208:211], v[152:155], 0
	v_mfma_f32_16x16x32_bf16 v[20:23], v[176:179], v[160:163], 0
	v_mfma_f32_16x16x32_bf16 v[16:19], v[208:211], v[160:163], 0
	v_mfma_f32_16x16x32_bf16 v[4:7], v[176:179], v[168:171], 0
	v_mfma_f32_16x16x32_bf16 v[0:3], v[208:211], v[168:171], 0
	v_mfma_f32_16x16x32_bf16 v[52:55], v[180:183], v[148:151], v[52:55]
	v_mfma_f32_16x16x32_bf16 v[48:51], v[212:215], v[148:151], v[48:51]
	v_mfma_f32_16x16x32_bf16 v[36:39], v[180:183], v[156:159], v[36:39]
	v_mfma_f32_16x16x32_bf16 v[32:35], v[212:215], v[156:159], v[32:35]
	v_mfma_f32_16x16x32_bf16 v[20:23], v[180:183], v[164:167], v[20:23]
	v_mfma_f32_16x16x32_bf16 v[16:19], v[212:215], v[164:167], v[16:19]
	v_mfma_f32_16x16x32_bf16 v[4:7], v[180:183], v[172:175], v[4:7]
	v_mfma_f32_16x16x32_bf16 v[0:3], v[212:215], v[172:175], v[0:3]
	s_add_i32 s53, 0, 0x18000
	v_add_u32_e32 v140, s53, v196
	s_barrier
	ds_read_b128 v[128:131], v140
	ds_read_b128 v[132:135], v140 offset:1024
	ds_read_b128 v[136:139], v140 offset:2048
	ds_read_b128 v[140:143], v140 offset:3072
	s_add_u32 s12, s14, 0x18000
	s_addc_u32 s13, s15, 0
	s_mov_b32 m0, s44
	ds_read_b128 v[144:147], v198 offset:32768
	ds_read_b128 v[148:151], v198 offset:33792
	ds_read_b128 v[152:155], v198 offset:34816
	ds_read_b128 v[156:159], v198 offset:35840
	ds_read_b128 v[160:163], v198 offset:36864
	ds_read_b128 v[164:167], v198 offset:37888
	ds_read_b128 v[168:171], v198 offset:38912
	ds_read_b128 v[172:175], v198 offset:39936
	global_load_lds_dwordx4 v186, s[12:13]
	s_mov_b32 m0, s45
	s_nop 0
	global_load_lds_dwordx4 v188, s[12:13]
	s_waitcnt lgkmcnt(8)
	s_barrier
	s_waitcnt lgkmcnt(0)
	v_mfma_f32_16x16x32_bf16 v[124:127], v[128:131], v[144:147], v[124:127]
	v_mfma_f32_16x16x32_bf16 v[120:123], v[136:139], v[144:147], v[120:123]
	v_mfma_f32_16x16x32_bf16 v[108:111], v[128:131], v[152:155], v[108:111]
	v_mfma_f32_16x16x32_bf16 v[104:107], v[136:139], v[152:155], v[104:107]
	v_mfma_f32_16x16x32_bf16 v[92:95], v[128:131], v[160:163], v[92:95]
	v_mfma_f32_16x16x32_bf16 v[88:91], v[136:139], v[160:163], v[88:91]
	v_mfma_f32_16x16x32_bf16 v[76:79], v[128:131], v[168:171], v[76:79]
	v_mfma_f32_16x16x32_bf16 v[72:75], v[136:139], v[168:171], v[72:75]
	v_mfma_f32_16x16x32_bf16 v[124:127], v[132:135], v[148:151], v[124:127]
	v_mfma_f32_16x16x32_bf16 v[120:123], v[140:143], v[148:151], v[120:123]
	v_mfma_f32_16x16x32_bf16 v[108:111], v[132:135], v[156:159], v[108:111]
	v_mfma_f32_16x16x32_bf16 v[104:107], v[140:143], v[156:159], v[104:107]
	v_mfma_f32_16x16x32_bf16 v[92:95], v[132:135], v[164:167], v[92:95]
	v_mfma_f32_16x16x32_bf16 v[88:91], v[140:143], v[164:167], v[88:91]
	v_mfma_f32_16x16x32_bf16 v[76:79], v[132:135], v[172:175], v[76:79]
	v_mfma_f32_16x16x32_bf16 v[72:75], v[140:143], v[172:175], v[72:75]
	s_barrier
	s_add_i32 s12, 0, 0x1c000
	s_add_i32 s13, s53, s41
	v_add_u32_e32 v192, s12, v196
	s_add_u32 s100, s10, 0x80
	s_addc_u32 s101, s11, 0
	s_mov_b32 m0, s13
	ds_read_b128 v[176:179], v192
	ds_read_b128 v[180:183], v192 offset:1024
	ds_read_b128 v[208:211], v192 offset:2048
	ds_read_b128 v[212:215], v192 offset:3072
	global_load_lds_dwordx4 v186, s[100:101]
	s_add_i32 m0, s13, 0x2000
	s_nop 0
	global_load_lds_dwordx4 v188, s[100:101]
	s_barrier
	s_waitcnt lgkmcnt(0)
	v_mfma_f32_16x16x32_bf16 v[116:119], v[176:179], v[144:147], v[116:119]
	v_mfma_f32_16x16x32_bf16 v[112:115], v[208:211], v[144:147], v[112:115]
	v_mfma_f32_16x16x32_bf16 v[100:103], v[176:179], v[152:155], v[100:103]
	v_mfma_f32_16x16x32_bf16 v[96:99], v[208:211], v[152:155], v[96:99]
	v_mfma_f32_16x16x32_bf16 v[84:87], v[176:179], v[160:163], v[84:87]
	v_mfma_f32_16x16x32_bf16 v[80:83], v[208:211], v[160:163], v[80:83]
	v_mfma_f32_16x16x32_bf16 v[68:71], v[176:179], v[168:171], v[68:71]
	v_mfma_f32_16x16x32_bf16 v[64:67], v[208:211], v[168:171], v[64:67]
	v_mfma_f32_16x16x32_bf16 v[116:119], v[180:183], v[148:151], v[116:119]
	v_mfma_f32_16x16x32_bf16 v[112:115], v[212:215], v[148:151], v[112:115]
	v_mfma_f32_16x16x32_bf16 v[100:103], v[180:183], v[156:159], v[100:103]
	v_mfma_f32_16x16x32_bf16 v[96:99], v[212:215], v[156:159], v[96:99]
	v_mfma_f32_16x16x32_bf16 v[84:87], v[180:183], v[164:167], v[84:87]
	v_mfma_f32_16x16x32_bf16 v[80:83], v[212:215], v[164:167], v[80:83]
	v_mfma_f32_16x16x32_bf16 v[68:71], v[180:183], v[172:175], v[68:71]
	v_mfma_f32_16x16x32_bf16 v[64:67], v[212:215], v[172:175], v[64:67]
	s_mov_b32 m0, s46
	s_add_u32 s100, s14, 0x80
	s_addc_u32 s101, s15, 0
	s_barrier
	ds_read_b128 v[144:147], v198 offset:49152
	ds_read_b128 v[148:151], v198 offset:50176
	ds_read_b128 v[152:155], v198 offset:51200
	ds_read_b128 v[156:159], v198 offset:52224
	ds_read_b128 v[160:163], v198 offset:53248
	ds_read_b128 v[164:167], v198 offset:54272
	ds_read_b128 v[168:171], v198 offset:55296
	ds_read_b128 v[172:175], v198 offset:56320
	global_load_lds_dwordx4 v186, s[100:101]
	s_mov_b32 m0, s47
	s_nop 0
	global_load_lds_dwordx4 v188, s[100:101]
	s_barrier
	s_waitcnt lgkmcnt(0)
	v_mfma_f32_16x16x32_bf16 v[60:63], v[128:131], v[144:147], v[60:63]
	v_mfma_f32_16x16x32_bf16 v[56:59], v[136:139], v[144:147], v[56:59]
	v_mfma_f32_16x16x32_bf16 v[44:47], v[128:131], v[152:155], v[44:47]
	v_mfma_f32_16x16x32_bf16 v[40:43], v[136:139], v[152:155], v[40:43]
	v_mfma_f32_16x16x32_bf16 v[28:31], v[128:131], v[160:163], v[28:31]
	v_mfma_f32_16x16x32_bf16 v[24:27], v[136:139], v[160:163], v[24:27]
	v_mfma_f32_16x16x32_bf16 v[12:15], v[128:131], v[168:171], v[12:15]
	v_mfma_f32_16x16x32_bf16 v[8:11], v[136:139], v[168:171], v[8:11]
	v_mfma_f32_16x16x32_bf16 v[60:63], v[132:135], v[148:151], v[60:63]
	v_mfma_f32_16x16x32_bf16 v[56:59], v[140:143], v[148:151], v[56:59]
	v_mfma_f32_16x16x32_bf16 v[44:47], v[132:135], v[156:159], v[44:47]
	v_mfma_f32_16x16x32_bf16 v[40:43], v[140:143], v[156:159], v[40:43]
	v_mfma_f32_16x16x32_bf16 v[28:31], v[132:135], v[164:167], v[28:31]
	v_mfma_f32_16x16x32_bf16 v[24:27], v[140:143], v[164:167], v[24:27]
	v_mfma_f32_16x16x32_bf16 v[12:15], v[132:135], v[172:175], v[12:15]
	v_mfma_f32_16x16x32_bf16 v[8:11], v[140:143], v[172:175], v[8:11]
	s_barrier
	s_add_u32 s10, s10, 0x18080
	s_addc_u32 s11, s11, 0
	s_add_i32 s12, s12, s41
	s_mov_b32 m0, s12
	s_nop 0
	global_load_lds_dwordx4 v186, s[10:11]
	s_add_i32 m0, s12, 0x2000
	s_nop 0
	global_load_lds_dwordx4 v188, s[10:11]
	s_waitcnt vmcnt(6)
	s_barrier
	v_mfma_f32_16x16x32_bf16 v[52:55], v[176:179], v[144:147], v[52:55]
	v_mfma_f32_16x16x32_bf16 v[48:51], v[208:211], v[144:147], v[48:51]
	v_mfma_f32_16x16x32_bf16 v[36:39], v[176:179], v[152:155], v[36:39]
	v_mfma_f32_16x16x32_bf16 v[32:35], v[208:211], v[152:155], v[32:35]
	v_mfma_f32_16x16x32_bf16 v[20:23], v[176:179], v[160:163], v[20:23]
	v_mfma_f32_16x16x32_bf16 v[16:19], v[208:211], v[160:163], v[16:19]
	v_mfma_f32_16x16x32_bf16 v[4:7], v[176:179], v[168:171], v[4:7]
	v_mfma_f32_16x16x32_bf16 v[0:3], v[208:211], v[168:171], v[0:3]
	v_mfma_f32_16x16x32_bf16 v[52:55], v[180:183], v[148:151], v[52:55]
	v_mfma_f32_16x16x32_bf16 v[48:51], v[212:215], v[148:151], v[48:51]
	v_mfma_f32_16x16x32_bf16 v[36:39], v[180:183], v[156:159], v[36:39]
	v_mfma_f32_16x16x32_bf16 v[32:35], v[212:215], v[156:159], v[32:35]
	v_mfma_f32_16x16x32_bf16 v[20:23], v[180:183], v[164:167], v[20:23]
	v_mfma_f32_16x16x32_bf16 v[16:19], v[212:215], v[164:167], v[16:19]
	v_mfma_f32_16x16x32_bf16 v[4:7], v[180:183], v[172:175], v[4:7]
	v_mfma_f32_16x16x32_bf16 v[0:3], v[212:215], v[172:175], v[0:3]
	s_add_i32 s52, s52, 2
	s_add_u32 s33, s33, 0x100
	s_addc_u32 s51, s51, 0
	s_cmp_gt_u32 s52, 3
	s_mov_b64 s[12:13], s[8:9]
	s_barrier

.LBB0_2483:
	s_ashr_i32 s15, s14, 31
	v_mov_b64_e32 v[0:1], 0x100
	s_lshl_b64 s[0:1], s[14:15], 18
	v_cmp_lt_i64_e32 vcc, s[22:23], v[0:1]
	s_add_u32 s22, s41, s0
	s_addc_u32 s23, s42, s1
	s_and_b64 s[0:1], vcc, exec
	s_cselect_b32 s0, s23, s31
	s_cselect_b32 s1, s22, s30
	s_ashr_i32 s21, s20, 31
	s_lshl_b64 s[24:25], s[20:21], 18
	s_add_u32 s24, s43, s24
	s_addc_u32 s25, s44, s25
	s_and_b64 s[36:37], vcc, exec
	s_cselect_b32 s15, s25, s35
	s_cselect_b32 s21, s24, s34
	s_add_u32 s30, s30, 0x20080
	s_addc_u32 s31, s31, 0
	s_add_u32 s27, s34, 0x100
	s_addc_u32 s33, s35, 0
	s_mov_b32 s52, -2
	s_waitcnt vmcnt(0)
	s_add_u32 s34, s30, 0xfffe0080
	s_addc_u32 s35, s31, -1
	s_add_i32 s53, 0, 0x10000
	v_add_u32_e32 v140, s53, v196
	ds_read_b128 v[128:131], v140
	ds_read_b128 v[132:135], v140 offset:1024
	ds_read_b128 v[136:139], v140 offset:2048
	ds_read_b128 v[140:143], v140 offset:3072
	s_cmp_eq_u32 s52, 4
	s_cselect_b32 s37, s0, s35
	s_cselect_b32 s36, s1, s34
	s_cselect_b32 s35, s15, s33
	s_cselect_b32 s34, s21, s27
	s_add_i32 m0, s29, 0xc000
	ds_read_b128 v[144:147], v198
	ds_read_b128 v[148:151], v198 offset:1024
	ds_read_b128 v[152:155], v198 offset:2048
	ds_read_b128 v[156:159], v198 offset:3072
	ds_read_b128 v[160:163], v198 offset:4096
	ds_read_b128 v[164:167], v198 offset:5120
	ds_read_b128 v[168:171], v198 offset:6144
	ds_read_b128 v[172:175], v198 offset:7168
	global_load_lds_dwordx4 v212, s[30:31]
	s_add_i32 m0, s29, 0xe000
	s_nop 0
	global_load_lds_dwordx4 v214, s[30:31]
	s_waitcnt lgkmcnt(8)
	s_barrier
	s_waitcnt lgkmcnt(0)
	v_mfma_f32_16x16x32_bf16 v[124:127], v[128:131], v[144:147], 0
	v_mfma_f32_16x16x32_bf16 v[120:123], v[136:139], v[144:147], 0
	v_mfma_f32_16x16x32_bf16 v[108:111], v[128:131], v[152:155], 0
	v_mfma_f32_16x16x32_bf16 v[104:107], v[136:139], v[152:155], 0
	v_mfma_f32_16x16x32_bf16 v[92:95], v[128:131], v[160:163], 0
	v_mfma_f32_16x16x32_bf16 v[88:91], v[136:139], v[160:163], 0
	v_mfma_f32_16x16x32_bf16 v[76:79], v[128:131], v[168:171], 0
	v_mfma_f32_16x16x32_bf16 v[72:75], v[136:139], v[168:171], 0
	v_mfma_f32_16x16x32_bf16 v[124:127], v[132:135], v[148:151], v[124:127]
	v_mfma_f32_16x16x32_bf16 v[120:123], v[140:143], v[148:151], v[120:123]
	v_mfma_f32_16x16x32_bf16 v[108:111], v[132:135], v[156:159], v[108:111]
	v_mfma_f32_16x16x32_bf16 v[104:107], v[140:143], v[156:159], v[104:107]
	v_mfma_f32_16x16x32_bf16 v[92:95], v[132:135], v[164:167], v[92:95]
	v_mfma_f32_16x16x32_bf16 v[88:91], v[140:143], v[164:167], v[88:91]
	v_mfma_f32_16x16x32_bf16 v[76:79], v[132:135], v[172:175], v[76:79]
	v_mfma_f32_16x16x32_bf16 v[72:75], v[140:143], v[172:175], v[72:75]
	s_barrier
	s_add_i32 s56, 0, 0x14000
	s_add_i32 s53, s53, s45
	v_add_u32_e32 v188, s56, v196
	s_mov_b32 m0, s53
	ds_read_b128 v[176:179], v188
	ds_read_b128 v[180:183], v188 offset:1024
	ds_read_b128 v[184:187], v188 offset:2048
	ds_read_b128 v[188:191], v188 offset:3072
	global_load_lds_dwordx4 v192, s[34:35]
	s_add_i32 m0, s53, 0x2000
	s_nop 0
	global_load_lds_dwordx4 v210, s[34:35]
	s_barrier
	s_waitcnt lgkmcnt(0)
	v_mfma_f32_16x16x32_bf16 v[116:119], v[176:179], v[144:147], 0
	v_mfma_f32_16x16x32_bf16 v[112:115], v[184:187], v[144:147], 0
	v_mfma_f32_16x16x32_bf16 v[100:103], v[176:179], v[152:155], 0
	v_mfma_f32_16x16x32_bf16 v[96:99], v[184:187], v[152:155], 0
	v_mfma_f32_16x16x32_bf16 v[84:87], v[176:179], v[160:163], 0
	v_mfma_f32_16x16x32_bf16 v[80:83], v[184:187], v[160:163], 0
	v_mfma_f32_16x16x32_bf16 v[68:71], v[176:179], v[168:171], 0
	v_mfma_f32_16x16x32_bf16 v[64:67], v[184:187], v[168:171], 0
	v_mfma_f32_16x16x32_bf16 v[116:119], v[180:183], v[148:151], v[116:119]
	v_mfma_f32_16x16x32_bf16 v[112:115], v[188:191], v[148:151], v[112:115]
	v_mfma_f32_16x16x32_bf16 v[100:103], v[180:183], v[156:159], v[100:103]
	v_mfma_f32_16x16x32_bf16 v[96:99], v[188:191], v[156:159], v[96:99]
	v_mfma_f32_16x16x32_bf16 v[84:87], v[180:183], v[164:167], v[84:87]
	v_mfma_f32_16x16x32_bf16 v[80:83], v[188:191], v[164:167], v[80:83]
	v_mfma_f32_16x16x32_bf16 v[68:71], v[180:183], v[172:175], v[68:71]
	v_mfma_f32_16x16x32_bf16 v[64:67], v[188:191], v[172:175], v[64:67]
	s_mov_b32 m0, s29
	s_add_u32 vcc_lo, s36, 0x80
	s_addc_u32 vcc_hi, s37, 0
	s_barrier
	ds_read_b128 v[144:147], v198 offset:16384
	ds_read_b128 v[148:151], v198 offset:17408
	ds_read_b128 v[152:155], v198 offset:18432
	ds_read_b128 v[156:159], v198 offset:19456
	ds_read_b128 v[160:163], v198 offset:20480
	ds_read_b128 v[164:167], v198 offset:21504
	ds_read_b128 v[168:171], v198 offset:22528
	ds_read_b128 v[172:175], v198 offset:23552
	global_load_lds_dwordx4 v206, s[36:37]
	s_mov_b32 m0, s46
	s_nop 0
	global_load_lds_dwordx4 v208, s[36:37]
	s_barrier
	s_waitcnt lgkmcnt(0)
	v_mfma_f32_16x16x32_bf16 v[60:63], v[128:131], v[144:147], 0
	v_mfma_f32_16x16x32_bf16 v[56:59], v[136:139], v[144:147], 0
	v_mfma_f32_16x16x32_bf16 v[44:47], v[128:131], v[152:155], 0
	v_mfma_f32_16x16x32_bf16 v[40:43], v[136:139], v[152:155], 0
	v_mfma_f32_16x16x32_bf16 v[28:31], v[128:131], v[160:163], 0
	v_mfma_f32_16x16x32_bf16 v[24:27], v[136:139], v[160:163], 0
	v_mfma_f32_16x16x32_bf16 v[12:15], v[128:131], v[168:171], 0
	v_mfma_f32_16x16x32_bf16 v[8:11], v[136:139], v[168:171], 0
	v_mfma_f32_16x16x32_bf16 v[60:63], v[132:135], v[148:151], v[60:63]
	v_mfma_f32_16x16x32_bf16 v[56:59], v[140:143], v[148:151], v[56:59]
	v_mfma_f32_16x16x32_bf16 v[44:47], v[132:135], v[156:159], v[44:47]
	v_mfma_f32_16x16x32_bf16 v[40:43], v[140:143], v[156:159], v[40:43]
	v_mfma_f32_16x16x32_bf16 v[28:31], v[132:135], v[164:167], v[28:31]
	v_mfma_f32_16x16x32_bf16 v[24:27], v[140:143], v[164:167], v[24:27]
	v_mfma_f32_16x16x32_bf16 v[12:15], v[132:135], v[172:175], v[12:15]
	v_mfma_f32_16x16x32_bf16 v[8:11], v[140:143], v[172:175], v[8:11]
	s_barrier
	s_add_u32 s54, s34, 0x20000
	s_addc_u32 s55, s35, 0
	s_add_i32 s53, s56, s45
	s_mov_b32 m0, s53
	s_nop 0
	global_load_lds_dwordx4 v192, s[54:55]
	s_add_i32 m0, s53, 0x2000
	s_nop 0
	global_load_lds_dwordx4 v210, s[54:55]
	s_waitcnt vmcnt(6)
	s_barrier
	v_mfma_f32_16x16x32_bf16 v[52:55], v[176:179], v[144:147], 0
	v_mfma_f32_16x16x32_bf16 v[48:51], v[184:187], v[144:147], 0
	v_mfma_f32_16x16x32_bf16 v[36:39], v[176:179], v[152:155], 0
	v_mfma_f32_16x16x32_bf16 v[32:35], v[184:187], v[152:155], 0
	v_mfma_f32_16x16x32_bf16 v[20:23], v[176:179], v[160:163], 0
	v_mfma_f32_16x16x32_bf16 v[16:19], v[184:187], v[160:163], 0
	v_mfma_f32_16x16x32_bf16 v[4:7], v[176:179], v[168:171], 0
	v_mfma_f32_16x16x32_bf16 v[0:3], v[184:187], v[168:171], 0
	v_mfma_f32_16x16x32_bf16 v[52:55], v[180:183], v[148:151], v[52:55]
	v_mfma_f32_16x16x32_bf16 v[48:51], v[188:191], v[148:151], v[48:51]
	v_mfma_f32_16x16x32_bf16 v[36:39], v[180:183], v[156:159], v[36:39]
	v_mfma_f32_16x16x32_bf16 v[32:35], v[188:191], v[156:159], v[32:35]
	v_mfma_f32_16x16x32_bf16 v[20:23], v[180:183], v[164:167], v[20:23]
	v_mfma_f32_16x16x32_bf16 v[16:19], v[188:191], v[164:167], v[16:19]
	v_mfma_f32_16x16x32_bf16 v[4:7], v[180:183], v[172:175], v[4:7]
	v_mfma_f32_16x16x32_bf16 v[0:3], v[188:191], v[172:175], v[0:3]
	s_add_i32 s53, 0, 0x18000
	v_add_u32_e32 v140, s53, v196
	s_barrier
	ds_read_b128 v[128:131], v140
	ds_read_b128 v[132:135], v140 offset:1024
	ds_read_b128 v[136:139], v140 offset:2048
	ds_read_b128 v[140:143], v140 offset:3072
	s_add_u32 s36, s36, 0x20000
	s_addc_u32 s37, s37, 0
	s_mov_b32 m0, s47
	ds_read_b128 v[144:147], v198 offset:32768
	ds_read_b128 v[148:151], v198 offset:33792
	ds_read_b128 v[152:155], v198 offset:34816
	ds_read_b128 v[156:159], v198 offset:35840
	ds_read_b128 v[160:163], v198 offset:36864
	ds_read_b128 v[164:167], v198 offset:37888
	ds_read_b128 v[168:171], v198 offset:38912
	ds_read_b128 v[172:175], v198 offset:39936
	global_load_lds_dwordx4 v206, s[36:37]
	s_mov_b32 m0, s48
	s_nop 0
	global_load_lds_dwordx4 v208, s[36:37]
	s_waitcnt lgkmcnt(8)
	s_barrier
	s_waitcnt lgkmcnt(0)
	v_mfma_f32_16x16x32_bf16 v[124:127], v[128:131], v[144:147], v[124:127]
	v_mfma_f32_16x16x32_bf16 v[120:123], v[136:139], v[144:147], v[120:123]
	v_mfma_f32_16x16x32_bf16 v[108:111], v[128:131], v[152:155], v[108:111]
	v_mfma_f32_16x16x32_bf16 v[104:107], v[136:139], v[152:155], v[104:107]
	v_mfma_f32_16x16x32_bf16 v[92:95], v[128:131], v[160:163], v[92:95]
	v_mfma_f32_16x16x32_bf16 v[88:91], v[136:139], v[160:163], v[88:91]
	v_mfma_f32_16x16x32_bf16 v[76:79], v[128:131], v[168:171], v[76:79]
	v_mfma_f32_16x16x32_bf16 v[72:75], v[136:139], v[168:171], v[72:75]
	v_mfma_f32_16x16x32_bf16 v[124:127], v[132:135], v[148:151], v[124:127]
	v_mfma_f32_16x16x32_bf16 v[120:123], v[140:143], v[148:151], v[120:123]
	v_mfma_f32_16x16x32_bf16 v[108:111], v[132:135], v[156:159], v[108:111]
	v_mfma_f32_16x16x32_bf16 v[104:107], v[140:143], v[156:159], v[104:107]
	v_mfma_f32_16x16x32_bf16 v[92:95], v[132:135], v[164:167], v[92:95]
	v_mfma_f32_16x16x32_bf16 v[88:91], v[140:143], v[164:167], v[88:91]
	v_mfma_f32_16x16x32_bf16 v[76:79], v[132:135], v[172:175], v[76:79]
	v_mfma_f32_16x16x32_bf16 v[72:75], v[140:143], v[172:175], v[72:75]
	s_barrier
	s_add_i32 s36, 0, 0x1c000
	s_add_i32 s37, s53, s45
	v_add_u32_e32 v188, s36, v196
	s_add_u32 s100, s34, 0x80
	s_addc_u32 s101, s35, 0
	s_mov_b32 m0, s37
	ds_read_b128 v[176:179], v188
	ds_read_b128 v[180:183], v188 offset:1024
	ds_read_b128 v[184:187], v188 offset:2048
	ds_read_b128 v[188:191], v188 offset:3072
	global_load_lds_dwordx4 v192, s[100:101]
	s_add_i32 m0, s37, 0x2000
	s_nop 0
	global_load_lds_dwordx4 v210, s[100:101]
	s_barrier
	s_waitcnt lgkmcnt(0)
	v_mfma_f32_16x16x32_bf16 v[116:119], v[176:179], v[144:147], v[116:119]
	v_mfma_f32_16x16x32_bf16 v[112:115], v[184:187], v[144:147], v[112:115]
	v_mfma_f32_16x16x32_bf16 v[100:103], v[176:179], v[152:155], v[100:103]
	v_mfma_f32_16x16x32_bf16 v[96:99], v[184:187], v[152:155], v[96:99]
	v_mfma_f32_16x16x32_bf16 v[84:87], v[176:179], v[160:163], v[84:87]
	v_mfma_f32_16x16x32_bf16 v[80:83], v[184:187], v[160:163], v[80:83]
	v_mfma_f32_16x16x32_bf16 v[68:71], v[176:179], v[168:171], v[68:71]
	v_mfma_f32_16x16x32_bf16 v[64:67], v[184:187], v[168:171], v[64:67]
	v_mfma_f32_16x16x32_bf16 v[116:119], v[180:183], v[148:151], v[116:119]
	v_mfma_f32_16x16x32_bf16 v[112:115], v[188:191], v[148:151], v[112:115]
	v_mfma_f32_16x16x32_bf16 v[100:103], v[180:183], v[156:159], v[100:103]
	v_mfma_f32_16x16x32_bf16 v[96:99], v[188:191], v[156:159], v[96:99]
	v_mfma_f32_16x16x32_bf16 v[84:87], v[180:183], v[164:167], v[84:87]
	v_mfma_f32_16x16x32_bf16 v[80:83], v[188:191], v[164:167], v[80:83]
	v_mfma_f32_16x16x32_bf16 v[68:71], v[180:183], v[172:175], v[68:71]
	v_mfma_f32_16x16x32_bf16 v[64:67], v[188:191], v[172:175], v[64:67]
	s_mov_b32 m0, s49
	s_barrier
	ds_read_b128 v[144:147], v198 offset:49152
	ds_read_b128 v[148:151], v198 offset:50176
	ds_read_b128 v[152:155], v198 offset:51200
	ds_read_b128 v[156:159], v198 offset:52224
	ds_read_b128 v[160:163], v198 offset:53248
	ds_read_b128 v[164:167], v198 offset:54272
	ds_read_b128 v[168:171], v198 offset:55296
	ds_read_b128 v[172:175], v198 offset:56320
	global_load_lds_dwordx4 v206, vcc
	s_mov_b32 m0, s50
	s_nop 0
	global_load_lds_dwordx4 v208, vcc
	s_barrier
	s_waitcnt lgkmcnt(0)
	v_mfma_f32_16x16x32_bf16 v[60:63], v[128:131], v[144:147], v[60:63]
	v_mfma_f32_16x16x32_bf16 v[56:59], v[136:139], v[144:147], v[56:59]
	v_mfma_f32_16x16x32_bf16 v[44:47], v[128:131], v[152:155], v[44:47]
	v_mfma_f32_16x16x32_bf16 v[40:43], v[136:139], v[152:155], v[40:43]
	v_mfma_f32_16x16x32_bf16 v[28:31], v[128:131], v[160:163], v[28:31]
	v_mfma_f32_16x16x32_bf16 v[24:27], v[136:139], v[160:163], v[24:27]
	v_mfma_f32_16x16x32_bf16 v[12:15], v[128:131], v[168:171], v[12:15]
	v_mfma_f32_16x16x32_bf16 v[8:11], v[136:139], v[168:171], v[8:11]
	v_mfma_f32_16x16x32_bf16 v[60:63], v[132:135], v[148:151], v[60:63]
	v_mfma_f32_16x16x32_bf16 v[56:59], v[140:143], v[148:151], v[56:59]
	v_mfma_f32_16x16x32_bf16 v[44:47], v[132:135], v[156:159], v[44:47]
	v_mfma_f32_16x16x32_bf16 v[40:43], v[140:143], v[156:159], v[40:43]
	v_mfma_f32_16x16x32_bf16 v[28:31], v[132:135], v[164:167], v[28:31]
	v_mfma_f32_16x16x32_bf16 v[24:27], v[140:143], v[164:167], v[24:27]
	v_mfma_f32_16x16x32_bf16 v[12:15], v[132:135], v[172:175], v[12:15]
	v_mfma_f32_16x16x32_bf16 v[8:11], v[140:143], v[172:175], v[8:11]
	s_barrier
	s_add_u32 s34, s34, 0x20080
	s_addc_u32 s35, s35, 0
	s_add_i32 s36, s36, s45
	s_mov_b32 m0, s36
	s_nop 0
	global_load_lds_dwordx4 v192, s[34:35]
	s_add_i32 m0, s36, 0x2000
	s_nop 0
	global_load_lds_dwordx4 v210, s[34:35]
	s_waitcnt vmcnt(6)
	s_barrier
	v_mfma_f32_16x16x32_bf16 v[52:55], v[176:179], v[144:147], v[52:55]
	v_mfma_f32_16x16x32_bf16 v[48:51], v[184:187], v[144:147], v[48:51]
	v_mfma_f32_16x16x32_bf16 v[36:39], v[176:179], v[152:155], v[36:39]
	v_mfma_f32_16x16x32_bf16 v[32:35], v[184:187], v[152:155], v[32:35]
	v_mfma_f32_16x16x32_bf16 v[20:23], v[176:179], v[160:163], v[20:23]
	v_mfma_f32_16x16x32_bf16 v[16:19], v[184:187], v[160:163], v[16:19]
	v_mfma_f32_16x16x32_bf16 v[4:7], v[176:179], v[168:171], v[4:7]
	v_mfma_f32_16x16x32_bf16 v[0:3], v[184:187], v[168:171], v[0:3]
	v_mfma_f32_16x16x32_bf16 v[52:55], v[180:183], v[148:151], v[52:55]
	v_mfma_f32_16x16x32_bf16 v[48:51], v[188:191], v[148:151], v[48:51]
	v_mfma_f32_16x16x32_bf16 v[36:39], v[180:183], v[156:159], v[36:39]
	v_mfma_f32_16x16x32_bf16 v[32:35], v[188:191], v[156:159], v[32:35]
	v_mfma_f32_16x16x32_bf16 v[20:23], v[180:183], v[164:167], v[20:23]
	v_mfma_f32_16x16x32_bf16 v[16:19], v[188:191], v[164:167], v[16:19]
	v_mfma_f32_16x16x32_bf16 v[4:7], v[180:183], v[172:175], v[4:7]
	v_mfma_f32_16x16x32_bf16 v[0:3], v[188:191], v[172:175], v[0:3]
	s_add_i32 s52, s52, 2
	s_add_u32 s30, s30, 0x100
	s_addc_u32 s31, s31, 0
	s_add_u32 s27, s27, 0x100
	s_addc_u32 s33, s33, 0
	s_cmp_gt_u32 s52, 5
	s_barrier

.LBB0_3617:
	s_add_u32 s33, s20, 0x100
	s_addc_u32 s43, s21, 0
	s_mov_b32 s44, -2
	s_waitcnt vmcnt(0)
	v_add_u32_e32 v202, 0x10000, v196
	v_add_u32_e32 v203, 0x14000, v196
	v_add_u32_e32 v204, 0x18000, v196
	v_add_u32_e32 v205, 0x1c000, v196
	s_add_u32 s20, s18, 0x100
	s_addc_u32 s21, s19, 0
	s_add_i32 s45, 0, 0x10000
	ds_read_b128 v[128:131], v202
	ds_read_b128 v[132:135], v202 offset:1024
	ds_read_b128 v[136:139], v202 offset:2048
	ds_read_b128 v[140:143], v202 offset:3072
	s_cmp_eq_u32 s44, 40
	s_cselect_b32 s25, s5, s21
	s_cselect_b32 s24, s4, s20
	s_cselect_b32 s23, s7, s43
	s_cselect_b32 s22, s6, s33
	s_add_i32 m0, s30, 0xc000
	ds_read_b128 v[144:147], v198
	ds_read_b128 v[148:151], v198 offset:1024
	ds_read_b128 v[152:155], v198 offset:2048
	ds_read_b128 v[156:159], v198 offset:3072
	ds_read_b128 v[160:163], v198 offset:4096
	ds_read_b128 v[164:167], v198 offset:5120
	ds_read_b128 v[168:171], v198 offset:6144
	ds_read_b128 v[172:175], v198 offset:7168
	global_load_lds_dwordx4 v214, s[18:19]
	s_add_i32 m0, s30, 0xe000
	s_nop 0
	global_load_lds_dwordx4 v212, s[18:19]
	s_waitcnt lgkmcnt(8)
	s_barrier
	s_waitcnt lgkmcnt(0)
	v_mfma_f32_16x16x32_bf16 v[124:127], v[128:131], v[144:147], 0
	v_mfma_f32_16x16x32_bf16 v[120:123], v[136:139], v[144:147], 0
	v_mfma_f32_16x16x32_bf16 v[108:111], v[128:131], v[152:155], 0
	v_mfma_f32_16x16x32_bf16 v[104:107], v[136:139], v[152:155], 0
	v_mfma_f32_16x16x32_bf16 v[92:95], v[128:131], v[160:163], 0
	v_mfma_f32_16x16x32_bf16 v[88:91], v[136:139], v[160:163], 0
	v_mfma_f32_16x16x32_bf16 v[76:79], v[128:131], v[168:171], 0
	v_mfma_f32_16x16x32_bf16 v[72:75], v[136:139], v[168:171], 0
	v_mfma_f32_16x16x32_bf16 v[124:127], v[132:135], v[148:151], v[124:127]
	v_mfma_f32_16x16x32_bf16 v[120:123], v[140:143], v[148:151], v[120:123]
	v_mfma_f32_16x16x32_bf16 v[108:111], v[132:135], v[156:159], v[108:111]
	v_mfma_f32_16x16x32_bf16 v[104:107], v[140:143], v[156:159], v[104:107]
	v_mfma_f32_16x16x32_bf16 v[92:95], v[132:135], v[164:167], v[92:95]
	v_mfma_f32_16x16x32_bf16 v[88:91], v[140:143], v[164:167], v[88:91]
	v_mfma_f32_16x16x32_bf16 v[76:79], v[132:135], v[172:175], v[76:79]
	v_mfma_f32_16x16x32_bf16 v[72:75], v[140:143], v[172:175], v[72:75]
	s_barrier
	s_add_i32 s46, 0, 0x14000
	s_add_i32 s18, s45, s29
	s_mov_b32 m0, s18
	ds_read_b128 v[176:179], v203
	ds_read_b128 v[180:183], v203 offset:1024
	ds_read_b128 v[184:187], v203 offset:2048
	ds_read_b128 v[188:191], v203 offset:3072
	global_load_lds_dwordx4 v192, s[22:23]
	s_add_i32 m0, s18, 0x2000
	s_nop 0
	global_load_lds_dwordx4 v210, s[22:23]
	s_barrier
	s_waitcnt lgkmcnt(0)
	v_mfma_f32_16x16x32_bf16 v[116:119], v[176:179], v[144:147], 0
	v_mfma_f32_16x16x32_bf16 v[112:115], v[184:187], v[144:147], 0
	v_mfma_f32_16x16x32_bf16 v[100:103], v[176:179], v[152:155], 0
	v_mfma_f32_16x16x32_bf16 v[96:99], v[184:187], v[152:155], 0
	v_mfma_f32_16x16x32_bf16 v[84:87], v[176:179], v[160:163], 0
	v_mfma_f32_16x16x32_bf16 v[80:83], v[184:187], v[160:163], 0
	v_mfma_f32_16x16x32_bf16 v[68:71], v[176:179], v[168:171], 0
	v_mfma_f32_16x16x32_bf16 v[64:67], v[184:187], v[168:171], 0
	v_mfma_f32_16x16x32_bf16 v[116:119], v[180:183], v[148:151], v[116:119]
	v_mfma_f32_16x16x32_bf16 v[112:115], v[188:191], v[148:151], v[112:115]
	v_mfma_f32_16x16x32_bf16 v[100:103], v[180:183], v[156:159], v[100:103]
	v_mfma_f32_16x16x32_bf16 v[96:99], v[188:191], v[156:159], v[96:99]
	v_mfma_f32_16x16x32_bf16 v[84:87], v[180:183], v[164:167], v[84:87]
	v_mfma_f32_16x16x32_bf16 v[80:83], v[188:191], v[164:167], v[80:83]
	v_mfma_f32_16x16x32_bf16 v[68:71], v[180:183], v[172:175], v[68:71]
	v_mfma_f32_16x16x32_bf16 v[64:67], v[188:191], v[172:175], v[64:67]
	s_mov_b32 m0, s30
	s_add_u32 vcc_lo, s24, 0x80
	s_addc_u32 vcc_hi, s25, 0
	s_barrier
	ds_read_b128 v[144:147], v198 offset:16384
	ds_read_b128 v[148:151], v198 offset:17408
	ds_read_b128 v[152:155], v198 offset:18432
	ds_read_b128 v[156:159], v198 offset:19456
	ds_read_b128 v[160:163], v198 offset:20480
	ds_read_b128 v[164:167], v198 offset:21504
	ds_read_b128 v[168:171], v198 offset:22528
	ds_read_b128 v[172:175], v198 offset:23552
	global_load_lds_dwordx4 v206, s[24:25]
	s_mov_b32 m0, s31
	s_nop 0
	global_load_lds_dwordx4 v208, s[24:25]
	s_barrier
	s_waitcnt lgkmcnt(0)
	v_mfma_f32_16x16x32_bf16 v[60:63], v[128:131], v[144:147], 0
	v_mfma_f32_16x16x32_bf16 v[56:59], v[136:139], v[144:147], 0
	v_mfma_f32_16x16x32_bf16 v[44:47], v[128:131], v[152:155], 0
	v_mfma_f32_16x16x32_bf16 v[40:43], v[136:139], v[152:155], 0
	v_mfma_f32_16x16x32_bf16 v[28:31], v[128:131], v[160:163], 0
	v_mfma_f32_16x16x32_bf16 v[24:27], v[136:139], v[160:163], 0
	v_mfma_f32_16x16x32_bf16 v[12:15], v[128:131], v[168:171], 0
	v_mfma_f32_16x16x32_bf16 v[8:11], v[136:139], v[168:171], 0
	v_mfma_f32_16x16x32_bf16 v[60:63], v[132:135], v[148:151], v[60:63]
	v_mfma_f32_16x16x32_bf16 v[56:59], v[140:143], v[148:151], v[56:59]
	v_mfma_f32_16x16x32_bf16 v[44:47], v[132:135], v[156:159], v[44:47]
	v_mfma_f32_16x16x32_bf16 v[40:43], v[140:143], v[156:159], v[40:43]
	v_mfma_f32_16x16x32_bf16 v[28:31], v[132:135], v[164:167], v[28:31]
	v_mfma_f32_16x16x32_bf16 v[24:27], v[140:143], v[164:167], v[24:27]
	v_mfma_f32_16x16x32_bf16 v[12:15], v[132:135], v[172:175], v[12:15]
	v_mfma_f32_16x16x32_bf16 v[8:11], v[140:143], v[172:175], v[8:11]
	s_barrier
	s_add_u32 s18, s22, 0xb0000
	s_addc_u32 s19, s23, 0
	s_add_i32 s45, s46, s29
	s_mov_b32 m0, s45
	s_nop 0
	global_load_lds_dwordx4 v192, s[18:19]
	s_add_i32 m0, s45, 0x2000
	s_nop 0
	global_load_lds_dwordx4 v210, s[18:19]
	s_waitcnt vmcnt(6)
	s_barrier
	v_mfma_f32_16x16x32_bf16 v[52:55], v[176:179], v[144:147], 0
	v_mfma_f32_16x16x32_bf16 v[48:51], v[184:187], v[144:147], 0
	v_mfma_f32_16x16x32_bf16 v[36:39], v[176:179], v[152:155], 0
	v_mfma_f32_16x16x32_bf16 v[32:35], v[184:187], v[152:155], 0
	v_mfma_f32_16x16x32_bf16 v[20:23], v[176:179], v[160:163], 0
	v_mfma_f32_16x16x32_bf16 v[16:19], v[184:187], v[160:163], 0
	v_mfma_f32_16x16x32_bf16 v[4:7], v[176:179], v[168:171], 0
	v_mfma_f32_16x16x32_bf16 v[0:3], v[184:187], v[168:171], 0
	v_mfma_f32_16x16x32_bf16 v[52:55], v[180:183], v[148:151], v[52:55]
	v_mfma_f32_16x16x32_bf16 v[48:51], v[188:191], v[148:151], v[48:51]
	v_mfma_f32_16x16x32_bf16 v[36:39], v[180:183], v[156:159], v[36:39]
	v_mfma_f32_16x16x32_bf16 v[32:35], v[188:191], v[156:159], v[32:35]
	v_mfma_f32_16x16x32_bf16 v[20:23], v[180:183], v[164:167], v[20:23]
	v_mfma_f32_16x16x32_bf16 v[16:19], v[188:191], v[164:167], v[16:19]
	v_mfma_f32_16x16x32_bf16 v[4:7], v[180:183], v[172:175], v[4:7]
	v_mfma_f32_16x16x32_bf16 v[0:3], v[188:191], v[172:175], v[0:3]
	s_add_i32 s45, 0, 0x18000
	s_barrier
	ds_read_b128 v[128:131], v204
	ds_read_b128 v[132:135], v204 offset:1024
	ds_read_b128 v[136:139], v204 offset:2048
	ds_read_b128 v[140:143], v204 offset:3072
	s_add_u32 s18, s24, 0xb0000
	s_addc_u32 s19, s25, 0
	s_mov_b32 m0, s34
	ds_read_b128 v[144:147], v198 offset:32768
	ds_read_b128 v[148:151], v198 offset:33792
	ds_read_b128 v[152:155], v198 offset:34816
	ds_read_b128 v[156:159], v198 offset:35840
	ds_read_b128 v[160:163], v198 offset:36864
	ds_read_b128 v[164:167], v198 offset:37888
	ds_read_b128 v[168:171], v198 offset:38912
	ds_read_b128 v[172:175], v198 offset:39936
	global_load_lds_dwordx4 v206, s[18:19]
	s_mov_b32 m0, s35
	s_nop 0
	global_load_lds_dwordx4 v208, s[18:19]
	s_waitcnt lgkmcnt(8)
	s_barrier
	s_waitcnt lgkmcnt(0)
	v_mfma_f32_16x16x32_bf16 v[124:127], v[128:131], v[144:147], v[124:127]
	v_mfma_f32_16x16x32_bf16 v[120:123], v[136:139], v[144:147], v[120:123]
	v_mfma_f32_16x16x32_bf16 v[108:111], v[128:131], v[152:155], v[108:111]
	v_mfma_f32_16x16x32_bf16 v[104:107], v[136:139], v[152:155], v[104:107]
	v_mfma_f32_16x16x32_bf16 v[92:95], v[128:131], v[160:163], v[92:95]
	v_mfma_f32_16x16x32_bf16 v[88:91], v[136:139], v[160:163], v[88:91]
	v_mfma_f32_16x16x32_bf16 v[76:79], v[128:131], v[168:171], v[76:79]
	v_mfma_f32_16x16x32_bf16 v[72:75], v[136:139], v[168:171], v[72:75]
	v_mfma_f32_16x16x32_bf16 v[124:127], v[132:135], v[148:151], v[124:127]
	v_mfma_f32_16x16x32_bf16 v[120:123], v[140:143], v[148:151], v[120:123]
	v_mfma_f32_16x16x32_bf16 v[108:111], v[132:135], v[156:159], v[108:111]
	v_mfma_f32_16x16x32_bf16 v[104:107], v[140:143], v[156:159], v[104:107]
	v_mfma_f32_16x16x32_bf16 v[92:95], v[132:135], v[164:167], v[92:95]
	v_mfma_f32_16x16x32_bf16 v[88:91], v[140:143], v[164:167], v[88:91]
	v_mfma_f32_16x16x32_bf16 v[76:79], v[132:135], v[172:175], v[76:79]
	v_mfma_f32_16x16x32_bf16 v[72:75], v[140:143], v[172:175], v[72:75]
	s_barrier
	s_add_i32 s24, 0, 0x1c000
	s_add_i32 s18, s45, s29
	s_add_u32 s100, s22, 0x80
	s_addc_u32 s101, s23, 0
	s_mov_b32 m0, s18
	ds_read_b128 v[176:179], v205
	ds_read_b128 v[180:183], v205 offset:1024
	ds_read_b128 v[184:187], v205 offset:2048
	ds_read_b128 v[188:191], v205 offset:3072
	global_load_lds_dwordx4 v192, s[100:101]
	s_add_i32 m0, s18, 0x2000
	s_nop 0
	global_load_lds_dwordx4 v210, s[100:101]
	s_barrier
	s_waitcnt lgkmcnt(0)
	v_mfma_f32_16x16x32_bf16 v[116:119], v[176:179], v[144:147], v[116:119]
	v_mfma_f32_16x16x32_bf16 v[112:115], v[184:187], v[144:147], v[112:115]
	v_mfma_f32_16x16x32_bf16 v[100:103], v[176:179], v[152:155], v[100:103]
	v_mfma_f32_16x16x32_bf16 v[96:99], v[184:187], v[152:155], v[96:99]
	v_mfma_f32_16x16x32_bf16 v[84:87], v[176:179], v[160:163], v[84:87]
	v_mfma_f32_16x16x32_bf16 v[80:83], v[184:187], v[160:163], v[80:83]
	v_mfma_f32_16x16x32_bf16 v[68:71], v[176:179], v[168:171], v[68:71]
	v_mfma_f32_16x16x32_bf16 v[64:67], v[184:187], v[168:171], v[64:67]
	v_mfma_f32_16x16x32_bf16 v[116:119], v[180:183], v[148:151], v[116:119]
	v_mfma_f32_16x16x32_bf16 v[112:115], v[188:191], v[148:151], v[112:115]
	v_mfma_f32_16x16x32_bf16 v[100:103], v[180:183], v[156:159], v[100:103]
	v_mfma_f32_16x16x32_bf16 v[96:99], v[188:191], v[156:159], v[96:99]
	v_mfma_f32_16x16x32_bf16 v[84:87], v[180:183], v[164:167], v[84:87]
	v_mfma_f32_16x16x32_bf16 v[80:83], v[188:191], v[164:167], v[80:83]
	v_mfma_f32_16x16x32_bf16 v[68:71], v[180:183], v[172:175], v[68:71]
	v_mfma_f32_16x16x32_bf16 v[64:67], v[188:191], v[172:175], v[64:67]
	s_mov_b32 m0, s36
	s_barrier
	ds_read_b128 v[144:147], v198 offset:49152
	ds_read_b128 v[148:151], v198 offset:50176
	ds_read_b128 v[152:155], v198 offset:51200
	ds_read_b128 v[156:159], v198 offset:52224
	ds_read_b128 v[160:163], v198 offset:53248
	ds_read_b128 v[164:167], v198 offset:54272
	ds_read_b128 v[168:171], v198 offset:55296
	ds_read_b128 v[172:175], v198 offset:56320
	global_load_lds_dwordx4 v206, vcc
	s_mov_b32 m0, s37
	s_nop 0
	global_load_lds_dwordx4 v208, vcc
	s_barrier
	s_waitcnt lgkmcnt(0)
	v_mfma_f32_16x16x32_bf16 v[60:63], v[128:131], v[144:147], v[60:63]
	v_mfma_f32_16x16x32_bf16 v[56:59], v[136:139], v[144:147], v[56:59]
	v_mfma_f32_16x16x32_bf16 v[44:47], v[128:131], v[152:155], v[44:47]
	v_mfma_f32_16x16x32_bf16 v[40:43], v[136:139], v[152:155], v[40:43]
	v_mfma_f32_16x16x32_bf16 v[28:31], v[128:131], v[160:163], v[28:31]
	v_mfma_f32_16x16x32_bf16 v[24:27], v[136:139], v[160:163], v[24:27]
	v_mfma_f32_16x16x32_bf16 v[12:15], v[128:131], v[168:171], v[12:15]
	v_mfma_f32_16x16x32_bf16 v[8:11], v[136:139], v[168:171], v[8:11]
	v_mfma_f32_16x16x32_bf16 v[60:63], v[132:135], v[148:151], v[60:63]
	v_mfma_f32_16x16x32_bf16 v[56:59], v[140:143], v[148:151], v[56:59]
	v_mfma_f32_16x16x32_bf16 v[44:47], v[132:135], v[156:159], v[44:47]
	v_mfma_f32_16x16x32_bf16 v[40:43], v[140:143], v[156:159], v[40:43]
	v_mfma_f32_16x16x32_bf16 v[28:31], v[132:135], v[164:167], v[28:31]
	v_mfma_f32_16x16x32_bf16 v[24:27], v[140:143], v[164:167], v[24:27]
	v_mfma_f32_16x16x32_bf16 v[12:15], v[132:135], v[172:175], v[12:15]
	v_mfma_f32_16x16x32_bf16 v[8:11], v[140:143], v[172:175], v[8:11]
	s_barrier
	s_add_u32 s18, s22, 0xb0080
	s_addc_u32 s19, s23, 0
	s_add_i32 s22, s24, s29
	s_mov_b32 m0, s22
	s_nop 0
	global_load_lds_dwordx4 v192, s[18:19]
	s_add_i32 m0, s22, 0x2000
	s_nop 0
	global_load_lds_dwordx4 v210, s[18:19]
	s_waitcnt vmcnt(6)
	s_barrier
	v_mfma_f32_16x16x32_bf16 v[52:55], v[176:179], v[144:147], v[52:55]
	v_mfma_f32_16x16x32_bf16 v[48:51], v[184:187], v[144:147], v[48:51]
	v_mfma_f32_16x16x32_bf16 v[36:39], v[176:179], v[152:155], v[36:39]
	v_mfma_f32_16x16x32_bf16 v[32:35], v[184:187], v[152:155], v[32:35]
	v_mfma_f32_16x16x32_bf16 v[20:23], v[176:179], v[160:163], v[20:23]
	v_mfma_f32_16x16x32_bf16 v[16:19], v[184:187], v[160:163], v[16:19]
	v_mfma_f32_16x16x32_bf16 v[4:7], v[176:179], v[168:171], v[4:7]
	v_mfma_f32_16x16x32_bf16 v[0:3], v[184:187], v[168:171], v[0:3]
	v_mfma_f32_16x16x32_bf16 v[52:55], v[180:183], v[148:151], v[52:55]
	v_mfma_f32_16x16x32_bf16 v[48:51], v[188:191], v[148:151], v[48:51]
	v_mfma_f32_16x16x32_bf16 v[36:39], v[180:183], v[156:159], v[36:39]
	v_mfma_f32_16x16x32_bf16 v[32:35], v[188:191], v[156:159], v[32:35]
	v_mfma_f32_16x16x32_bf16 v[20:23], v[180:183], v[164:167], v[20:23]
	v_mfma_f32_16x16x32_bf16 v[16:19], v[188:191], v[164:167], v[16:19]
	v_mfma_f32_16x16x32_bf16 v[4:7], v[180:183], v[172:175], v[4:7]
	v_mfma_f32_16x16x32_bf16 v[0:3], v[188:191], v[172:175], v[0:3]
	s_add_i32 s44, s44, 2
	s_add_u32 s33, s33, 0x100
	s_addc_u32 s43, s43, 0
	s_cmp_gt_u32 s44, 41
	s_mov_b64 s[18:19], s[20:21]
	s_barrier
